# attention P.V loops (A-layer mixer): the 4 V-fragment reads of each key-pair group hoisted above the probability packing into spare VGPRs, MFMAs back to back
# speedup vs baseline: 1.0146x; 1.0146x over previous
.LBB0_151:
	s_or_b64 exec, exec, s[10:11]
	v_and_b32_e32 v5, 64, v229
	v_mov_b32_e32 v1, v4
	v_xor_b32_e32 v4, 16, v229
	v_add_u32_e32 v5, 64, v5
	v_cmp_lt_i32_e32 vcc, v4, v5
	v_and_b32_e32 v71, 15, v52
	v_mad_u32_u24 v79, v71, s13, v72
	v_cndmask_b32_e32 v78, v229, v4, vcc
	v_xor_b32_e32 v4, 32, v229
	v_cmp_lt_i32_e32 vcc, v4, v5
	v_mov_b32_e32 v65, v6
	v_cndmask_b32_e32 v73, v229, v4, vcc
	v_lshlrev_b32_e32 v73, 2, v73
	ds_read_b128 v[116:119], v79
	ds_read_b128 v[120:123], v79 offset:64
	ds_read_b128 v[124:127], v79 offset:2304
	ds_read_b128 v[128:131], v79 offset:2368
	ds_read_b128 v[132:135], v79 offset:4608
	ds_read_b128 v[136:139], v79 offset:4672
	ds_read_b128 v[140:143], v79 offset:6912
	ds_read_b128 v[144:147], v79 offset:6976
	ds_read_b128 v[148:151], v79 offset:9216
	ds_read_b128 v[152:155], v79 offset:9280
	ds_read_b128 v[156:159], v79 offset:11520
	ds_read_b128 v[160:163], v79 offset:11584
	s_waitcnt lgkmcnt(6)
	v_mfma_f32_16x16x32_bf16 v[60:63], v[116:119], v[0:3], 0
	v_mfma_f32_16x16x32_bf16 v[56:59], v[124:127], v[0:3], 0
	v_mfma_f32_16x16x32_bf16 v[52:55], v[132:135], v[0:3], 0
	v_mfma_f32_16x16x32_bf16 v[60:63], v[120:123], v[64:67], v[60:63]
	v_mfma_f32_16x16x32_bf16 v[56:59], v[128:131], v[64:67], v[56:59]
	v_mfma_f32_16x16x32_bf16 v[52:55], v[136:139], v[64:67], v[52:55]
	ds_read_b128 v[116:119], v79 offset:13824
	ds_read_b128 v[120:123], v79 offset:13888
	ds_read_b128 v[124:127], v79 offset:16128
	ds_read_b128 v[128:131], v79 offset:16192
	ds_read_b128 v[132:135], v79 offset:18432
	ds_read_b128 v[136:139], v79 offset:18496
	s_waitcnt lgkmcnt(6)
	v_mfma_f32_16x16x32_bf16 v[48:51], v[140:143], v[0:3], 0
	v_mfma_f32_16x16x32_bf16 v[44:47], v[148:151], v[0:3], 0
	v_mfma_f32_16x16x32_bf16 v[40:43], v[156:159], v[0:3], 0
	v_mfma_f32_16x16x32_bf16 v[48:51], v[144:147], v[64:67], v[48:51]
	v_mfma_f32_16x16x32_bf16 v[44:47], v[152:155], v[64:67], v[44:47]
	v_mfma_f32_16x16x32_bf16 v[40:43], v[160:163], v[64:67], v[40:43]
	ds_read_b128 v[140:143], v79 offset:20736
	ds_read_b128 v[144:147], v79 offset:20800
	ds_read_b128 v[148:151], v79 offset:23040
	ds_read_b128 v[152:155], v79 offset:23104
	ds_read_b128 v[156:159], v79 offset:25344
	ds_read_b128 v[160:163], v79 offset:25408
	s_waitcnt lgkmcnt(6)
	v_mfma_f32_16x16x32_bf16 v[36:39], v[116:119], v[0:3], 0
	v_mfma_f32_16x16x32_bf16 v[32:35], v[124:127], v[0:3], 0
	v_mfma_f32_16x16x32_bf16 v[28:31], v[132:135], v[0:3], 0
	v_mfma_f32_16x16x32_bf16 v[36:39], v[120:123], v[64:67], v[36:39]
	v_mfma_f32_16x16x32_bf16 v[32:35], v[128:131], v[64:67], v[32:35]
	v_mfma_f32_16x16x32_bf16 v[28:31], v[136:139], v[64:67], v[28:31]
	ds_read_b128 v[116:119], v79 offset:27648
	ds_read_b128 v[120:123], v79 offset:27712
	ds_read_b128 v[124:127], v79 offset:29952
	ds_read_b128 v[128:131], v79 offset:30016
	ds_read_b128 v[132:135], v79 offset:32256
	ds_read_b128 v[136:139], v79 offset:32320
	s_waitcnt lgkmcnt(6)
	v_mfma_f32_16x16x32_bf16 v[24:27], v[140:143], v[0:3], 0
	v_mfma_f32_16x16x32_bf16 v[20:23], v[148:151], v[0:3], 0
	v_mfma_f32_16x16x32_bf16 v[16:19], v[156:159], v[0:3], 0
	v_mfma_f32_16x16x32_bf16 v[24:27], v[144:147], v[64:67], v[24:27]
	v_mfma_f32_16x16x32_bf16 v[20:23], v[152:155], v[64:67], v[20:23]
	v_mfma_f32_16x16x32_bf16 v[16:19], v[160:163], v[64:67], v[16:19]
	s_waitcnt lgkmcnt(0)
	v_mfma_f32_16x16x32_bf16 v[12:15], v[116:119], v[0:3], 0
	v_mfma_f32_16x16x32_bf16 v[8:11], v[124:127], v[0:3], 0
	v_mfma_f32_16x16x32_bf16 v[4:7], v[132:135], v[0:3], 0
	v_mfma_f32_16x16x32_bf16 v[12:15], v[120:123], v[64:67], v[12:15]
	v_mfma_f32_16x16x32_bf16 v[8:11], v[128:131], v[64:67], v[8:11]
	v_mfma_f32_16x16x32_bf16 v[4:7], v[136:139], v[64:67], v[4:7]
	ds_read_b128 v[116:119], v79 offset:34560
	ds_read_b128 v[120:123], v79 offset:34624
	s_waitcnt lgkmcnt(0)
	v_mfma_f32_16x16x32_bf16 v[124:127], v[116:119], v[0:3], 0
	v_mfma_f32_16x16x32_bf16 v[0:3], v[120:123], v[64:67], v[124:127]
	v_mul_f32_e32 v64, 0x3e000000, v60
	v_mul_f32_e32 v65, 0x3e000000, v61
	s_mov_b32 s2, 0xff61b1e6
	v_max3_f32 v64, v64, s2, v65
	v_mul_f32_e32 v65, 0x3e000000, v62
	v_mul_f32_e32 v66, 0x3e000000, v63
	v_max3_f32 v64, v64, v65, v66
	v_mul_f32_e32 v65, 0x3e000000, v56
	v_mul_f32_e32 v66, 0x3e000000, v57
	v_max3_f32 v64, v64, v65, v66
	v_mul_f32_e32 v65, 0x3e000000, v58
	v_mul_f32_e32 v66, 0x3e000000, v59
	v_max3_f32 v64, v64, v65, v66
	v_mul_f32_e32 v65, 0x3e000000, v52
	v_mul_f32_e32 v66, 0x3e000000, v53
	v_max3_f32 v64, v64, v65, v66
	v_mul_f32_e32 v65, 0x3e000000, v54
	v_mul_f32_e32 v66, 0x3e000000, v55
	v_max3_f32 v64, v64, v65, v66
	v_mul_f32_e32 v65, 0x3e000000, v48
	v_mul_f32_e32 v66, 0x3e000000, v49
	v_max3_f32 v64, v64, v65, v66
	v_mul_f32_e32 v65, 0x3e000000, v50
	v_mul_f32_e32 v66, 0x3e000000, v51
	v_max3_f32 v64, v64, v65, v66
	v_mul_f32_e32 v65, 0x3e000000, v44
	v_mul_f32_e32 v66, 0x3e000000, v45
	v_max3_f32 v64, v64, v65, v66
	v_mul_f32_e32 v65, 0x3e000000, v46
	v_mul_f32_e32 v66, 0x3e000000, v47
	v_max3_f32 v64, v64, v65, v66
	v_mul_f32_e32 v65, 0x3e000000, v40
	v_mul_f32_e32 v66, 0x3e000000, v41
	v_max3_f32 v64, v64, v65, v66
	v_mul_f32_e32 v65, 0x3e000000, v42
	v_mul_f32_e32 v66, 0x3e000000, v43
	v_max3_f32 v64, v64, v65, v66
	v_mul_f32_e32 v65, 0x3e000000, v36
	v_mul_f32_e32 v66, 0x3e000000, v37
	v_max3_f32 v64, v64, v65, v66
	v_mul_f32_e32 v65, 0x3e000000, v38
	v_mul_f32_e32 v66, 0x3e000000, v39
	v_max3_f32 v64, v64, v65, v66
	v_mul_f32_e32 v65, 0x3e000000, v32
	v_mul_f32_e32 v66, 0x3e000000, v33
	v_max3_f32 v64, v64, v65, v66
	v_mul_f32_e32 v65, 0x3e000000, v34
	v_mul_f32_e32 v66, 0x3e000000, v35
	v_max3_f32 v64, v64, v65, v66
	v_mul_f32_e32 v65, 0x3e000000, v28
	v_mul_f32_e32 v66, 0x3e000000, v29
	v_max3_f32 v64, v64, v65, v66
	v_mul_f32_e32 v65, 0x3e000000, v30
	v_mul_f32_e32 v66, 0x3e000000, v31
	v_max3_f32 v64, v64, v65, v66
	v_mul_f32_e32 v65, 0x3e000000, v24
	v_mul_f32_e32 v66, 0x3e000000, v25
	v_max3_f32 v64, v64, v65, v66
	v_mul_f32_e32 v65, 0x3e000000, v26
	v_mul_f32_e32 v66, 0x3e000000, v27
	v_max3_f32 v64, v64, v65, v66
	v_mul_f32_e32 v65, 0x3e000000, v20
	v_mul_f32_e32 v66, 0x3e000000, v21
	v_max3_f32 v64, v64, v65, v66
	v_mul_f32_e32 v65, 0x3e000000, v22
	v_mul_f32_e32 v66, 0x3e000000, v23
	v_max3_f32 v64, v64, v65, v66
	v_mul_f32_e32 v65, 0x3e000000, v16
	v_mul_f32_e32 v66, 0x3e000000, v17
	v_max3_f32 v64, v64, v65, v66
	v_mul_f32_e32 v65, 0x3e000000, v18
	v_mul_f32_e32 v66, 0x3e000000, v19
	v_max3_f32 v64, v64, v65, v66
	v_mul_f32_e32 v65, 0x3e000000, v12
	v_mul_f32_e32 v66, 0x3e000000, v13
	v_max3_f32 v64, v64, v65, v66
	v_mul_f32_e32 v65, 0x3e000000, v14
	v_mul_f32_e32 v66, 0x3e000000, v15
	v_max3_f32 v64, v64, v65, v66
	v_mul_f32_e32 v65, 0x3e000000, v8
	v_mul_f32_e32 v66, 0x3e000000, v9
	v_max3_f32 v64, v64, v65, v66
	v_mul_f32_e32 v65, 0x3e000000, v10
	v_mul_f32_e32 v66, 0x3e000000, v11
	v_max3_f32 v64, v64, v65, v66
	v_mul_f32_e32 v65, 0x3e000000, v4
	v_mul_f32_e32 v66, 0x3e000000, v5
	v_max3_f32 v64, v64, v65, v66
	v_mul_f32_e32 v65, 0x3e000000, v6
	v_mul_f32_e32 v66, 0x3e000000, v7
	v_max3_f32 v64, v64, v65, v66
	v_mul_f32_e32 v65, 0x3e000000, v0
	v_mul_f32_e32 v66, 0x3e000000, v1
	v_max3_f32 v64, v64, v65, v66
	v_mul_f32_e32 v65, 0x3e000000, v2
	v_mul_f32_e32 v66, 0x3e000000, v3
	v_max3_f32 v64, v64, v65, v66
	v_lshlrev_b32_e32 v74, 2, v78
	ds_bpermute_b32 v65, v74, v64
	s_mov_b32 s2, 0x3e000000
	v_sub_u32_e32 v72, v72, v70
	s_waitcnt lgkmcnt(0)
	v_max_f32_e32 v65, v65, v65
	v_max_f32_e32 v64, v64, v65
	ds_bpermute_b32 v65, v73, v64
	s_waitcnt lgkmcnt(0)
	v_max_f32_e32 v65, v65, v65
	v_max_f32_e32 v75, v64, v65
	v_fma_f32 v60, v60, s2, -v75
	v_fma_f32 v61, v61, s2, -v75
	v_mul_f32_e32 v60, 0x3fb8aa3b, v60
	v_mul_f32_e32 v61, 0x3fb8aa3b, v61
	v_exp_f32_e32 v60, v60
	v_exp_f32_e32 v64, v61
	v_fma_f32 v61, v62, s2, -v75
	v_mul_f32_e32 v61, 0x3fb8aa3b, v61
	v_exp_f32_e32 v61, v61
	v_add_f32_e32 v65, 0, v60
	v_fma_f32 v63, v63, s2, -v75
	v_add_f32_e32 v65, v64, v65
	v_mul_f32_e32 v63, 0x3fb8aa3b, v63
	v_add_f32_e32 v62, v61, v65
	v_exp_f32_e32 v65, v63
	v_fma_f32 v56, v56, s2, -v75
	v_mul_f32_e32 v56, 0x3fb8aa3b, v56
	v_fma_f32 v57, v57, s2, -v75
	v_add_f32_e32 v63, v65, v62
	v_exp_f32_e32 v62, v56
	v_mul_f32_e32 v57, 0x3fb8aa3b, v57
	v_exp_f32_e32 v66, v57
	v_fma_f32 v57, v58, s2, -v75
	v_mul_f32_e32 v57, 0x3fb8aa3b, v57
	v_add_f32_e32 v56, v62, v63
	v_exp_f32_e32 v63, v57
	v_fma_f32 v57, v59, s2, -v75
	v_mul_f32_e32 v57, 0x3fb8aa3b, v57
	v_fma_f32 v52, v52, s2, -v75
	v_exp_f32_e32 v67, v57
	v_mul_f32_e32 v52, 0x3fb8aa3b, v52
	v_exp_f32_e32 v52, v52
	v_add_f32_e32 v56, v66, v56
	v_add_f32_e32 v56, v63, v56
	v_fma_f32 v53, v53, s2, -v75
	v_add_f32_e32 v56, v67, v56
	v_mul_f32_e32 v53, 0x3fb8aa3b, v53
	v_add_f32_e32 v57, v52, v56
	v_exp_f32_e32 v56, v53
	v_fma_f32 v53, v54, s2, -v75
	v_mul_f32_e32 v53, 0x3fb8aa3b, v53
	v_exp_f32_e32 v53, v53
	v_fma_f32 v55, v55, s2, -v75
	v_add_f32_e32 v57, v56, v57
	v_mul_f32_e32 v55, 0x3fb8aa3b, v55
	v_add_f32_e32 v54, v53, v57
	v_exp_f32_e32 v57, v55
	v_fma_f32 v48, v48, s2, -v75
	v_mul_f32_e32 v48, 0x3fb8aa3b, v48
	v_fma_f32 v49, v49, s2, -v75
	v_add_f32_e32 v55, v57, v54
	v_exp_f32_e32 v54, v48
	v_mul_f32_e32 v49, 0x3fb8aa3b, v49
	v_exp_f32_e32 v58, v49
	v_fma_f32 v49, v50, s2, -v75
	v_mul_f32_e32 v49, 0x3fb8aa3b, v49
	v_add_f32_e32 v48, v54, v55
	v_exp_f32_e32 v55, v49
	v_fma_f32 v49, v51, s2, -v75
	v_mul_f32_e32 v49, 0x3fb8aa3b, v49
	v_fma_f32 v44, v44, s2, -v75
	v_exp_f32_e32 v59, v49
	v_mul_f32_e32 v44, 0x3fb8aa3b, v44
	v_exp_f32_e32 v44, v44
	v_add_f32_e32 v48, v58, v48
	v_add_f32_e32 v48, v55, v48
	v_fma_f32 v45, v45, s2, -v75
	v_add_f32_e32 v48, v59, v48
	v_mul_f32_e32 v45, 0x3fb8aa3b, v45
	v_add_f32_e32 v49, v44, v48
	v_exp_f32_e32 v48, v45
	v_fma_f32 v45, v46, s2, -v75
	v_mul_f32_e32 v45, 0x3fb8aa3b, v45
	v_exp_f32_e32 v45, v45
	v_fma_f32 v47, v47, s2, -v75
	v_add_f32_e32 v49, v48, v49
	v_mul_f32_e32 v47, 0x3fb8aa3b, v47
	v_add_f32_e32 v46, v45, v49
	v_exp_f32_e32 v49, v47
	v_fma_f32 v40, v40, s2, -v75
	v_mul_f32_e32 v40, 0x3fb8aa3b, v40
	v_fma_f32 v41, v41, s2, -v75
	v_add_f32_e32 v47, v49, v46
	v_exp_f32_e32 v46, v40
	v_mul_f32_e32 v41, 0x3fb8aa3b, v41
	v_exp_f32_e32 v50, v41
	v_fma_f32 v41, v42, s2, -v75
	v_mul_f32_e32 v41, 0x3fb8aa3b, v41
	v_add_f32_e32 v40, v46, v47
	v_exp_f32_e32 v47, v41
	v_fma_f32 v41, v43, s2, -v75
	v_mul_f32_e32 v41, 0x3fb8aa3b, v41
	v_fma_f32 v36, v36, s2, -v75
	v_exp_f32_e32 v51, v41
	v_mul_f32_e32 v36, 0x3fb8aa3b, v36
	v_exp_f32_e32 v36, v36
	v_add_f32_e32 v40, v50, v40
	v_add_f32_e32 v40, v47, v40
	v_fma_f32 v37, v37, s2, -v75
	v_add_f32_e32 v40, v51, v40
	v_mul_f32_e32 v37, 0x3fb8aa3b, v37
	v_add_f32_e32 v41, v36, v40
	v_exp_f32_e32 v40, v37
	v_fma_f32 v37, v38, s2, -v75
	v_mul_f32_e32 v37, 0x3fb8aa3b, v37
	v_exp_f32_e32 v37, v37
	v_fma_f32 v39, v39, s2, -v75
	v_add_f32_e32 v41, v40, v41
	v_mul_f32_e32 v39, 0x3fb8aa3b, v39
	v_add_f32_e32 v38, v37, v41
	v_exp_f32_e32 v41, v39
	v_fma_f32 v32, v32, s2, -v75
	v_mul_f32_e32 v32, 0x3fb8aa3b, v32
	v_fma_f32 v33, v33, s2, -v75
	v_add_f32_e32 v39, v41, v38
	v_exp_f32_e32 v38, v32
	v_mul_f32_e32 v33, 0x3fb8aa3b, v33
	v_exp_f32_e32 v42, v33
	v_fma_f32 v33, v34, s2, -v75
	v_mul_f32_e32 v33, 0x3fb8aa3b, v33
	v_add_f32_e32 v32, v38, v39
	v_exp_f32_e32 v39, v33
	v_fma_f32 v33, v35, s2, -v75
	v_mul_f32_e32 v33, 0x3fb8aa3b, v33
	v_fma_f32 v28, v28, s2, -v75
	v_exp_f32_e32 v43, v33
	v_mul_f32_e32 v28, 0x3fb8aa3b, v28
	v_exp_f32_e32 v28, v28
	v_add_f32_e32 v32, v42, v32
	v_add_f32_e32 v32, v39, v32
	v_fma_f32 v29, v29, s2, -v75
	v_add_f32_e32 v32, v43, v32
	v_mul_f32_e32 v29, 0x3fb8aa3b, v29
	v_add_f32_e32 v33, v28, v32
	v_exp_f32_e32 v32, v29
	v_fma_f32 v29, v30, s2, -v75
	v_mul_f32_e32 v29, 0x3fb8aa3b, v29
	v_exp_f32_e32 v29, v29
	v_fma_f32 v31, v31, s2, -v75
	v_add_f32_e32 v33, v32, v33
	v_mul_f32_e32 v31, 0x3fb8aa3b, v31
	v_add_f32_e32 v30, v29, v33
	v_exp_f32_e32 v33, v31
	v_fma_f32 v24, v24, s2, -v75
	v_mul_f32_e32 v24, 0x3fb8aa3b, v24
	v_fma_f32 v25, v25, s2, -v75
	v_add_f32_e32 v31, v33, v30
	v_exp_f32_e32 v30, v24
	v_mul_f32_e32 v25, 0x3fb8aa3b, v25
	v_exp_f32_e32 v34, v25
	v_fma_f32 v25, v26, s2, -v75
	v_mul_f32_e32 v25, 0x3fb8aa3b, v25
	v_add_f32_e32 v24, v30, v31
	v_exp_f32_e32 v31, v25
	v_fma_f32 v25, v27, s2, -v75
	v_mul_f32_e32 v25, 0x3fb8aa3b, v25
	v_fma_f32 v20, v20, s2, -v75
	v_exp_f32_e32 v35, v25
	v_mul_f32_e32 v20, 0x3fb8aa3b, v20
	v_exp_f32_e32 v20, v20
	v_add_f32_e32 v24, v34, v24
	v_add_f32_e32 v24, v31, v24
	v_fma_f32 v21, v21, s2, -v75
	v_add_f32_e32 v24, v35, v24
	v_mul_f32_e32 v21, 0x3fb8aa3b, v21
	v_add_f32_e32 v25, v20, v24
	v_exp_f32_e32 v24, v21
	v_fma_f32 v21, v22, s2, -v75
	v_mul_f32_e32 v21, 0x3fb8aa3b, v21
	v_exp_f32_e32 v21, v21
	v_fma_f32 v23, v23, s2, -v75
	v_add_f32_e32 v25, v24, v25
	v_mul_f32_e32 v23, 0x3fb8aa3b, v23
	v_add_f32_e32 v22, v21, v25
	v_exp_f32_e32 v25, v23
	v_fma_f32 v16, v16, s2, -v75
	v_mul_f32_e32 v16, 0x3fb8aa3b, v16
	v_fma_f32 v17, v17, s2, -v75
	v_add_f32_e32 v23, v25, v22
	v_exp_f32_e32 v22, v16
	v_mul_f32_e32 v17, 0x3fb8aa3b, v17
	v_exp_f32_e32 v26, v17
	v_fma_f32 v17, v18, s2, -v75
	v_mul_f32_e32 v17, 0x3fb8aa3b, v17
	v_add_f32_e32 v16, v22, v23
	v_exp_f32_e32 v23, v17
	v_fma_f32 v17, v19, s2, -v75
	v_mul_f32_e32 v17, 0x3fb8aa3b, v17
	v_fma_f32 v12, v12, s2, -v75
	v_exp_f32_e32 v27, v17
	v_mul_f32_e32 v12, 0x3fb8aa3b, v12
	v_exp_f32_e32 v12, v12
	v_add_f32_e32 v16, v26, v16
	v_add_f32_e32 v16, v23, v16
	v_fma_f32 v13, v13, s2, -v75
	v_add_f32_e32 v16, v27, v16
	v_mul_f32_e32 v13, 0x3fb8aa3b, v13
	v_add_f32_e32 v17, v12, v16
	v_exp_f32_e32 v16, v13
	v_fma_f32 v13, v14, s2, -v75
	v_mul_f32_e32 v13, 0x3fb8aa3b, v13
	v_exp_f32_e32 v13, v13
	v_fma_f32 v15, v15, s2, -v75
	v_add_f32_e32 v17, v16, v17
	v_mul_f32_e32 v15, 0x3fb8aa3b, v15
	v_add_f32_e32 v14, v13, v17
	v_exp_f32_e32 v17, v15
	v_fma_f32 v8, v8, s2, -v75
	v_mul_f32_e32 v8, 0x3fb8aa3b, v8
	v_fma_f32 v9, v9, s2, -v75
	v_add_f32_e32 v15, v17, v14
	v_exp_f32_e32 v14, v8
	v_mul_f32_e32 v9, 0x3fb8aa3b, v9
	v_exp_f32_e32 v18, v9
	v_fma_f32 v9, v10, s2, -v75
	v_mul_f32_e32 v9, 0x3fb8aa3b, v9
	v_add_f32_e32 v8, v14, v15
	v_exp_f32_e32 v15, v9
	v_fma_f32 v9, v11, s2, -v75
	v_mul_f32_e32 v9, 0x3fb8aa3b, v9
	v_fma_f32 v4, v4, s2, -v75
	v_exp_f32_e32 v19, v9
	v_mul_f32_e32 v4, 0x3fb8aa3b, v4
	v_exp_f32_e32 v4, v4
	v_add_f32_e32 v8, v18, v8
	v_add_f32_e32 v8, v15, v8
	v_fma_f32 v5, v5, s2, -v75
	v_add_f32_e32 v8, v19, v8
	v_mul_f32_e32 v5, 0x3fb8aa3b, v5
	v_add_f32_e32 v9, v4, v8
	v_exp_f32_e32 v8, v5
	v_fma_f32 v5, v6, s2, -v75
	v_mul_f32_e32 v5, 0x3fb8aa3b, v5
	v_exp_f32_e32 v5, v5
	v_fma_f32 v7, v7, s2, -v75
	v_add_f32_e32 v9, v8, v9
	v_mul_f32_e32 v7, 0x3fb8aa3b, v7
	v_fma_f32 v0, v0, s2, -v75
	v_add_f32_e32 v6, v5, v9
	v_exp_f32_e32 v9, v7
	v_mul_f32_e32 v0, 0x3fb8aa3b, v0
	v_exp_f32_e32 v0, v0
	v_fma_f32 v1, v1, s2, -v75
	v_add_f32_e32 v6, v9, v6
	v_mul_f32_e32 v1, 0x3fb8aa3b, v1
	v_add_f32_e32 v7, v0, v6
	v_exp_f32_e32 v6, v1
	v_fma_f32 v1, v2, s2, -v75
	v_mul_f32_e32 v1, 0x3fb8aa3b, v1
	v_exp_f32_e32 v1, v1
	v_fma_f32 v3, v3, s2, -v75
	v_add_f32_e32 v7, v6, v7
	v_mul_f32_e32 v3, 0x3fb8aa3b, v3
	v_add_f32_e32 v2, v1, v7
	v_exp_f32_e32 v7, v3
	s_nop 0
	v_add_f32_e32 v2, v7, v2
	ds_bpermute_b32 v3, v74, v2
	s_waitcnt lgkmcnt(0)
	v_add_f32_e32 v2, v2, v3
	ds_bpermute_b32 v3, v73, v2
	s_waitcnt lgkmcnt(0)
	v_add_f32_e32 v2, v2, v3
	v_div_scale_f32 v3, s[2:3], v2, v2, 1.0
	v_rcp_f32_e32 v10, v3
	v_div_scale_f32 v11, vcc, 1.0, v2, 1.0
	s_movk_i32 s2, 0x210
	v_fma_f32 v73, -v3, v10, 1.0
	v_fmac_f32_e32 v10, v73, v10
	v_mul_f32_e32 v73, v11, v10
	v_fma_f32 v74, -v3, v73, v11
	v_fmac_f32_e32 v73, v74, v10
	v_fma_f32 v3, -v3, v73, v11
	v_div_fmas_f32 v3, v3, v10, v73
	v_div_fixup_f32 v2, v3, v2, 1.0
	v_pk_mul_f32 v[10:11], v[60:61], v[2:3] op_sel_hi:[1,0]
	v_pk_mul_f32 v[60:61], v[64:65], v[2:3] op_sel_hi:[1,0]
	v_pk_mul_f32 v[64:65], v[66:67], v[2:3] op_sel_hi:[1,0]
	v_pk_mul_f32 v[62:63], v[62:63], v[2:3] op_sel_hi:[1,0]
	v_bfe_u32 v3, v65, 16, 1
	v_bfe_u32 v66, v64, 16, 1
	v_bfe_u32 v67, v61, 16, 1
	v_bfe_u32 v73, v60, 16, 1
	v_add3_u32 v65, v65, v3, s33
	v_bfe_u32 v3, v10, 16, 1
	v_mad_u32_u24 v71, v71, s2, v72
	v_add3_u32 v73, v60, v73, s33
	v_add3_u32 v74, v61, v67, s33
	v_add3_u32 v64, v64, v66, s33
	v_bfe_u32 v60, v11, 16, 1
	v_bfe_u32 v61, v62, 16, 1
	v_bfe_u32 v66, v63, 16, 1
	v_add3_u32 v10, v10, v3, s33
	v_add_u32_e32 v3, 0x9000, v71
	v_add3_u32 v66, v63, v66, s33
	v_add3_u32 v67, v62, v61, s33
	v_add3_u32 v11, v11, v60, s33
	ds_read2_b64 v[60:63], v3 offset1:4
	v_lshrrev_b32_e32 v10, 16, v10
	v_lshrrev_b32_e32 v11, 16, v11
	v_lshrrev_b32_e32 v72, 16, v67
	v_lshrrev_b32_e32 v66, 16, v66
	v_and_or_b32 v67, v65, s29, v66
	v_and_or_b32 v66, v64, s29, v72
	v_and_or_b32 v65, v74, s29, v11
	v_and_or_b32 v64, v73, s29, v10
	v_add_u32_e32 v10, 0xb000, v71
	s_waitcnt lgkmcnt(0)
	v_mfma_f32_16x16x32_bf16 v[72:75], v[60:63], v[64:67], 0
	ds_read2_b64 v[60:63], v10 offset0:32 offset1:36
	s_waitcnt lgkmcnt(0)
	v_mfma_f32_16x16x32_bf16 v[76:79], v[60:63], v[64:67], 0
	v_add_u32_e32 v60, 0xd000, v71
	v_add_u32_e32 v61, 0xf000, v71
	ds_read2_b64 v[82:85], v60 offset0:64 offset1:68
	ds_read2_b64 v[86:89], v61 offset0:96 offset1:100
	s_waitcnt lgkmcnt(1)
	v_mfma_f32_16x16x32_bf16 v[82:85], v[82:85], v[64:67], 0
	s_waitcnt lgkmcnt(0)
	v_mfma_f32_16x16x32_bf16 v[62:65], v[86:89], v[64:67], 0
	ds_read2_b64 v[116:119], v3 offset0:8 offset1:12
	ds_read2_b64 v[120:123], v10 offset0:40 offset1:44
	ds_read2_b64 v[124:127], v60 offset0:72 offset1:76
	ds_read2_b64 v[128:131], v61 offset0:104 offset1:108
	v_mul_f32_e64 v56, v56, v2
	v_mul_f32_e64 v57, v57, v2
	v_pk_mul_f32 v[58:59], v[58:59], v[2:3] op_sel_hi:[1,0]
	v_pk_mul_f32 v[52:53], v[52:53], v[2:3] op_sel_hi:[1,0]
	v_pk_mul_f32 v[54:55], v[54:55], v[2:3] op_sel_hi:[1,0]
	v_bfe_u32 v11, v59, 16, 1
	v_bfe_u32 v66, v58, 16, 1
	v_bfe_u32 v67, v57, 16, 1
	v_bfe_u32 v71, v56, 16, 1
	v_add3_u32 v56, v56, v71, s33
	v_add3_u32 v57, v57, v67, s33
	v_add3_u32 v58, v58, v66, s33
	v_add3_u32 v11, v59, v11, s33
	v_bfe_u32 v59, v52, 16, 1
	v_bfe_u32 v66, v53, 16, 1
	v_bfe_u32 v67, v54, 16, 1
	v_bfe_u32 v71, v55, 16, 1
	v_add3_u32 v71, v55, v71, s33
	v_add3_u32 v67, v54, v67, s33
	v_add3_u32 v66, v53, v66, s33
	v_add3_u32 v59, v52, v59, s33
	v_lshrrev_b32_e32 v81, 16, v59
	v_lshrrev_b32_e32 v66, 16, v66
	v_lshrrev_b32_e32 v67, 16, v67
	v_lshrrev_b32_e32 v59, 16, v71
	v_and_or_b32 v59, v11, s29, v59
	v_and_or_b32 v58, v58, s29, v67
	v_and_or_b32 v57, v57, s29, v66
	v_and_or_b32 v56, v56, s29, v81
	s_waitcnt lgkmcnt(3)
	s_nop 1
	v_mfma_f32_16x16x32_bf16 v[52:55], v[116:119], v[56:59], v[72:75]
	s_waitcnt lgkmcnt(2)
	v_mfma_f32_16x16x32_bf16 v[72:75], v[120:123], v[56:59], v[76:79]
	s_waitcnt lgkmcnt(1)
	v_mfma_f32_16x16x32_bf16 v[76:79], v[124:127], v[56:59], v[82:85]
	s_waitcnt lgkmcnt(0)
	v_mfma_f32_16x16x32_bf16 v[56:59], v[128:131], v[56:59], v[62:65]
	ds_read2_b64 v[132:135], v3 offset0:16 offset1:20
	ds_read2_b64 v[136:139], v10 offset0:48 offset1:52
	ds_read2_b64 v[140:143], v60 offset0:80 offset1:84
	ds_read2_b64 v[144:147], v61 offset0:112 offset1:116
	v_mul_f32_e64 v48, v48, v2
	v_mul_f32_e64 v49, v49, v2
	v_pk_mul_f32 v[50:51], v[50:51], v[2:3] op_sel_hi:[1,0]
	v_pk_mul_f32 v[44:45], v[44:45], v[2:3] op_sel_hi:[1,0]
	v_pk_mul_f32 v[46:47], v[46:47], v[2:3] op_sel_hi:[1,0]
	v_bfe_u32 v11, v51, 16, 1
	v_bfe_u32 v62, v50, 16, 1
	v_bfe_u32 v63, v49, 16, 1
	v_bfe_u32 v64, v48, 16, 1
	v_add3_u32 v48, v48, v64, s33
	v_add3_u32 v49, v49, v63, s33
	v_add3_u32 v50, v50, v62, s33
	v_add3_u32 v11, v51, v11, s33
	v_bfe_u32 v51, v44, 16, 1
	v_bfe_u32 v62, v45, 16, 1
	v_bfe_u32 v63, v46, 16, 1
	v_bfe_u32 v64, v47, 16, 1
	v_add3_u32 v64, v47, v64, s33
	v_add3_u32 v63, v46, v63, s33
	v_add3_u32 v62, v45, v62, s33
	v_add3_u32 v51, v44, v51, s33
	v_lshrrev_b32_e32 v65, 16, v51
	v_lshrrev_b32_e32 v62, 16, v62
	v_lshrrev_b32_e32 v63, 16, v63
	v_lshrrev_b32_e32 v51, 16, v64
	v_and_or_b32 v51, v11, s29, v51
	v_and_or_b32 v50, v50, s29, v63
	v_and_or_b32 v49, v49, s29, v62
	v_and_or_b32 v48, v48, s29, v65
	s_waitcnt lgkmcnt(3)
	s_nop 1
	v_mfma_f32_16x16x32_bf16 v[44:47], v[132:135], v[48:51], v[52:55]
	s_waitcnt lgkmcnt(2)
	v_mfma_f32_16x16x32_bf16 v[52:55], v[136:139], v[48:51], v[72:75]
	s_waitcnt lgkmcnt(1)
	v_mfma_f32_16x16x32_bf16 v[62:65], v[140:143], v[48:51], v[76:79]
	s_waitcnt lgkmcnt(0)
	v_mfma_f32_16x16x32_bf16 v[48:51], v[144:147], v[48:51], v[56:59]
	ds_read2_b64 v[116:119], v3 offset0:24 offset1:28
	ds_read2_b64 v[120:123], v10 offset0:56 offset1:60
	ds_read2_b64 v[124:127], v60 offset0:88 offset1:92
	ds_read2_b64 v[128:131], v61 offset0:120 offset1:124
	v_mul_f32_e64 v40, v40, v2
	v_mul_f32_e64 v41, v41, v2
	v_pk_mul_f32 v[42:43], v[42:43], v[2:3] op_sel_hi:[1,0]
	v_pk_mul_f32 v[36:37], v[36:37], v[2:3] op_sel_hi:[1,0]
	v_pk_mul_f32 v[38:39], v[38:39], v[2:3] op_sel_hi:[1,0]
	v_bfe_u32 v11, v43, 16, 1
	v_bfe_u32 v56, v42, 16, 1
	v_bfe_u32 v57, v41, 16, 1
	v_bfe_u32 v58, v40, 16, 1
	v_add3_u32 v40, v40, v58, s33
	v_add3_u32 v41, v41, v57, s33
	v_add3_u32 v42, v42, v56, s33
	v_add3_u32 v11, v43, v11, s33
	v_bfe_u32 v43, v36, 16, 1
	v_bfe_u32 v56, v37, 16, 1
	v_bfe_u32 v57, v38, 16, 1
	v_bfe_u32 v58, v39, 16, 1
	v_add3_u32 v58, v39, v58, s33
	v_add3_u32 v57, v38, v57, s33
	v_add3_u32 v56, v37, v56, s33
	v_add3_u32 v43, v36, v43, s33
	v_lshrrev_b32_e32 v59, 16, v43
	v_lshrrev_b32_e32 v56, 16, v56
	v_lshrrev_b32_e32 v57, 16, v57
	v_lshrrev_b32_e32 v43, 16, v58
	v_and_or_b32 v43, v11, s29, v43
	v_and_or_b32 v42, v42, s29, v57
	v_and_or_b32 v41, v41, s29, v56
	v_and_or_b32 v40, v40, s29, v59
	s_waitcnt lgkmcnt(3)
	s_nop 1
	v_mfma_f32_16x16x32_bf16 v[36:39], v[116:119], v[40:43], v[44:47]
	s_waitcnt lgkmcnt(2)
	v_mfma_f32_16x16x32_bf16 v[44:47], v[120:123], v[40:43], v[52:55]
	s_waitcnt lgkmcnt(1)
	v_mfma_f32_16x16x32_bf16 v[52:55], v[124:127], v[40:43], v[62:65]
	s_waitcnt lgkmcnt(0)
	v_mfma_f32_16x16x32_bf16 v[40:43], v[128:131], v[40:43], v[48:51]
	ds_read2_b64 v[132:135], v3 offset0:32 offset1:36
	ds_read2_b64 v[136:139], v10 offset0:64 offset1:68
	ds_read2_b64 v[140:143], v60 offset0:96 offset1:100
	ds_read2_b64 v[144:147], v61 offset0:128 offset1:132
	v_mul_f32_e64 v32, v32, v2
	v_mul_f32_e64 v33, v33, v2
	v_pk_mul_f32 v[34:35], v[34:35], v[2:3] op_sel_hi:[1,0]
	v_pk_mul_f32 v[28:29], v[28:29], v[2:3] op_sel_hi:[1,0]
	v_pk_mul_f32 v[30:31], v[30:31], v[2:3] op_sel_hi:[1,0]
	v_bfe_u32 v11, v35, 16, 1
	v_bfe_u32 v48, v34, 16, 1
	v_bfe_u32 v49, v33, 16, 1
	v_bfe_u32 v50, v32, 16, 1
	v_add3_u32 v32, v32, v50, s33
	v_add3_u32 v33, v33, v49, s33
	v_add3_u32 v34, v34, v48, s33
	v_add3_u32 v11, v35, v11, s33
	v_bfe_u32 v35, v28, 16, 1
	v_bfe_u32 v48, v29, 16, 1
	v_bfe_u32 v49, v30, 16, 1
	v_bfe_u32 v50, v31, 16, 1
	v_add3_u32 v50, v31, v50, s33
	v_add3_u32 v49, v30, v49, s33
	v_add3_u32 v48, v29, v48, s33
	v_add3_u32 v35, v28, v35, s33
	v_lshrrev_b32_e32 v51, 16, v35
	v_lshrrev_b32_e32 v48, 16, v48
	v_lshrrev_b32_e32 v49, 16, v49
	v_lshrrev_b32_e32 v35, 16, v50
	v_and_or_b32 v35, v11, s29, v35
	v_and_or_b32 v34, v34, s29, v49
	v_and_or_b32 v33, v33, s29, v48
	v_and_or_b32 v32, v32, s29, v51
	s_waitcnt lgkmcnt(3)
	s_nop 1
	v_mfma_f32_16x16x32_bf16 v[28:31], v[132:135], v[32:35], v[36:39]
	s_waitcnt lgkmcnt(2)
	v_mfma_f32_16x16x32_bf16 v[36:39], v[136:139], v[32:35], v[44:47]
	s_waitcnt lgkmcnt(1)
	v_mfma_f32_16x16x32_bf16 v[44:47], v[140:143], v[32:35], v[52:55]
	s_waitcnt lgkmcnt(0)
	v_mfma_f32_16x16x32_bf16 v[32:35], v[144:147], v[32:35], v[40:43]
	ds_read2_b64 v[116:119], v3 offset0:40 offset1:44
	ds_read2_b64 v[120:123], v10 offset0:72 offset1:76
	ds_read2_b64 v[124:127], v60 offset0:104 offset1:108
	ds_read2_b64 v[128:131], v61 offset0:136 offset1:140
	v_mul_f32_e64 v24, v24, v2
	v_mul_f32_e64 v25, v25, v2
	v_pk_mul_f32 v[26:27], v[26:27], v[2:3] op_sel_hi:[1,0]
	v_pk_mul_f32 v[20:21], v[20:21], v[2:3] op_sel_hi:[1,0]
	v_pk_mul_f32 v[22:23], v[22:23], v[2:3] op_sel_hi:[1,0]
	v_bfe_u32 v11, v27, 16, 1
	v_bfe_u32 v40, v26, 16, 1
	v_bfe_u32 v41, v25, 16, 1
	v_bfe_u32 v42, v24, 16, 1
	v_add3_u32 v24, v24, v42, s33
	v_add3_u32 v25, v25, v41, s33
	v_add3_u32 v26, v26, v40, s33
	v_add3_u32 v11, v27, v11, s33
	v_bfe_u32 v27, v20, 16, 1
	v_bfe_u32 v40, v21, 16, 1
	v_bfe_u32 v41, v22, 16, 1
	v_bfe_u32 v42, v23, 16, 1
	v_add3_u32 v42, v23, v42, s33
	v_add3_u32 v41, v22, v41, s33
	v_add3_u32 v40, v21, v40, s33
	v_add3_u32 v27, v20, v27, s33
	v_lshrrev_b32_e32 v43, 16, v27
	v_lshrrev_b32_e32 v40, 16, v40
	v_lshrrev_b32_e32 v41, 16, v41
	v_lshrrev_b32_e32 v27, 16, v42
	v_and_or_b32 v27, v11, s29, v27
	v_and_or_b32 v26, v26, s29, v41
	v_and_or_b32 v25, v25, s29, v40
	v_and_or_b32 v24, v24, s29, v43
	s_waitcnt lgkmcnt(3)
	s_nop 1
	v_mfma_f32_16x16x32_bf16 v[20:23], v[116:119], v[24:27], v[28:31]
	s_waitcnt lgkmcnt(2)
	v_mfma_f32_16x16x32_bf16 v[28:31], v[120:123], v[24:27], v[36:39]
	s_waitcnt lgkmcnt(1)
	v_mfma_f32_16x16x32_bf16 v[36:39], v[124:127], v[24:27], v[44:47]
	s_waitcnt lgkmcnt(0)
	v_mfma_f32_16x16x32_bf16 v[24:27], v[128:131], v[24:27], v[32:35]
	ds_read2_b64 v[132:135], v3 offset0:48 offset1:52
	ds_read2_b64 v[136:139], v10 offset0:80 offset1:84
	ds_read2_b64 v[140:143], v60 offset0:112 offset1:116
	ds_read2_b64 v[144:147], v61 offset0:144 offset1:148
	v_mul_f32_e64 v16, v16, v2
	v_mul_f32_e64 v17, v17, v2
	v_pk_mul_f32 v[18:19], v[18:19], v[2:3] op_sel_hi:[1,0]
	v_pk_mul_f32 v[12:13], v[12:13], v[2:3] op_sel_hi:[1,0]
	v_pk_mul_f32 v[14:15], v[14:15], v[2:3] op_sel_hi:[1,0]
	v_bfe_u32 v11, v19, 16, 1
	v_bfe_u32 v32, v18, 16, 1
	v_bfe_u32 v33, v17, 16, 1
	v_bfe_u32 v34, v16, 16, 1
	v_add3_u32 v16, v16, v34, s33
	v_add3_u32 v17, v17, v33, s33
	v_add3_u32 v18, v18, v32, s33
	v_add3_u32 v11, v19, v11, s33
	v_bfe_u32 v19, v12, 16, 1
	v_bfe_u32 v32, v13, 16, 1
	v_bfe_u32 v33, v14, 16, 1
	v_bfe_u32 v34, v15, 16, 1
	v_add3_u32 v34, v15, v34, s33
	v_add3_u32 v33, v14, v33, s33
	v_add3_u32 v32, v13, v32, s33
	v_add3_u32 v19, v12, v19, s33
	v_lshrrev_b32_e32 v35, 16, v19
	v_lshrrev_b32_e32 v32, 16, v32
	v_lshrrev_b32_e32 v33, 16, v33
	v_lshrrev_b32_e32 v19, 16, v34
	v_and_or_b32 v19, v11, s29, v19
	v_and_or_b32 v18, v18, s29, v33
	v_and_or_b32 v17, v17, s29, v32
	v_and_or_b32 v16, v16, s29, v35
	s_waitcnt lgkmcnt(3)
	s_nop 1
	v_mfma_f32_16x16x32_bf16 v[12:15], v[132:135], v[16:19], v[20:23]
	s_waitcnt lgkmcnt(2)
	v_mfma_f32_16x16x32_bf16 v[20:23], v[136:139], v[16:19], v[28:31]
	s_waitcnt lgkmcnt(1)
	v_mfma_f32_16x16x32_bf16 v[28:31], v[140:143], v[16:19], v[36:39]
	s_waitcnt lgkmcnt(0)
	v_mfma_f32_16x16x32_bf16 v[16:19], v[144:147], v[16:19], v[24:27]
	ds_read2_b64 v[116:119], v3 offset0:56 offset1:60
	ds_read2_b64 v[120:123], v10 offset0:88 offset1:92
	ds_read2_b64 v[124:127], v60 offset0:120 offset1:124
	ds_read2_b64 v[128:131], v61 offset0:152 offset1:156
	v_mul_f32_e64 v8, v8, v2
	v_mul_f32_e64 v9, v9, v2
	v_pk_mul_f32 v[6:7], v[6:7], v[2:3] op_sel_hi:[1,0]
	v_pk_mul_f32 v[4:5], v[4:5], v[2:3] op_sel_hi:[1,0]
	v_pk_mul_f32 v[0:1], v[0:1], v[2:3] op_sel_hi:[1,0]
	v_bfe_u32 v2, v7, 16, 1
	v_bfe_u32 v24, v9, 16, 1
	v_bfe_u32 v25, v8, 16, 1
	v_add3_u32 v8, v8, v25, s33
	v_add3_u32 v9, v9, v24, s33
	v_add3_u32 v7, v7, v2, s33
	v_bfe_u32 v2, v4, 16, 1
	v_bfe_u32 v24, v0, 16, 1
	v_bfe_u32 v25, v1, 16, 1
	v_add3_u32 v25, v1, v25, s33
	v_add3_u32 v24, v0, v24, s33
	v_add3_u32 v4, v4, v2, s33
	v_bfe_u32 v11, v6, 16, 1
	v_add3_u32 v6, v6, v11, s33
	v_bfe_u32 v11, v5, 16, 1
	v_add3_u32 v5, v5, v11, s33
	v_lshrrev_b32_e32 v4, 16, v4
	v_lshrrev_b32_e32 v5, 16, v5
	v_lshrrev_b32_e32 v11, 16, v24
	v_lshrrev_b32_e32 v24, 16, v25
	v_and_or_b32 v27, v7, s29, v24
	v_and_or_b32 v26, v6, s29, v11
	v_and_or_b32 v25, v9, s29, v5
	v_and_or_b32 v24, v8, s29, v4
	s_waitcnt lgkmcnt(3)
	s_nop 1
	v_mfma_f32_16x16x32_bf16 v[12:15], v[116:119], v[24:27], v[12:15]
	s_waitcnt lgkmcnt(2)
	v_mfma_f32_16x16x32_bf16 v[8:11], v[120:123], v[24:27], v[20:23]
	s_waitcnt lgkmcnt(1)
	v_mfma_f32_16x16x32_bf16 v[4:7], v[124:127], v[24:27], v[28:31]
	s_waitcnt lgkmcnt(0)
	v_mfma_f32_16x16x32_bf16 v[0:3], v[128:131], v[24:27], v[16:19]
	s_and_b64 exec, exec, s[0:1]
	s_cbranch_execz .LBB0_153
	s_lshl_b32 s0, s17, 11
	v_bfe_u32 v18, v12, 16, 1
	s_add_u32 s0, s6, s0
	v_add3_u32 v12, v12, v18, s33
	v_bfe_u32 v18, v13, 16, 1
	s_addc_u32 s1, s7, 0
	v_add3_u32 v13, v13, v18, s33
	v_lshrrev_b32_e32 v12, 16, v12
	s_add_u32 s0, s0, s12
	v_and_or_b32 v12, v13, s29, v12
	v_bfe_u32 v13, v14, 16, 1
	s_addc_u32 s1, s1, 0
	v_lshlrev_b64 v[16:17], 11, v[68:69]
	v_add3_u32 v13, v14, v13, s33
	v_bfe_u32 v14, v15, 16, 1
	v_lshl_add_u64 v[16:17], s[0:1], 0, v[16:17]
	v_mov_b32_e32 v71, v80
	v_add3_u32 v14, v15, v14, s33
	v_lshrrev_b32_e32 v13, 16, v13
	v_lshl_add_u64 v[16:17], v[16:17], 0, v[70:71]
	v_and_or_b32 v13, v14, s29, v13
	global_store_dwordx2 v[16:17], v[12:13], off offset:1536
	v_bfe_u32 v12, v8, 16, 1
	v_add3_u32 v8, v8, v12, s33
	v_bfe_u32 v12, v9, 16, 1
	v_add3_u32 v9, v9, v12, s33
	v_lshrrev_b32_e32 v8, 16, v8
	v_and_or_b32 v8, v9, s29, v8
	v_bfe_u32 v9, v10, 16, 1
	v_add3_u32 v9, v10, v9, s33
	v_bfe_u32 v10, v11, 16, 1
	v_add3_u32 v10, v11, v10, s33
	v_lshrrev_b32_e32 v9, 16, v9
	v_and_or_b32 v9, v10, s29, v9
	global_store_dwordx2 v[16:17], v[8:9], off offset:1568
	v_bfe_u32 v8, v4, 16, 1
	v_add3_u32 v4, v4, v8, s33
	v_bfe_u32 v8, v5, 16, 1
	v_add3_u32 v5, v5, v8, s33
	v_lshrrev_b32_e32 v4, 16, v4
	v_and_or_b32 v4, v5, s29, v4
	v_bfe_u32 v5, v6, 16, 1
	v_add3_u32 v5, v6, v5, s33
	v_bfe_u32 v6, v7, 16, 1
	v_add3_u32 v6, v7, v6, s33
	v_lshrrev_b32_e32 v5, 16, v5
	v_and_or_b32 v5, v6, s29, v5
	global_store_dwordx2 v[16:17], v[4:5], off offset:1600
	v_bfe_u32 v4, v0, 16, 1
	v_add3_u32 v0, v0, v4, s33
	v_bfe_u32 v4, v1, 16, 1
	v_add3_u32 v1, v1, v4, s33
	v_lshrrev_b32_e32 v0, 16, v0
	v_and_or_b32 v0, v1, s29, v0
	v_bfe_u32 v1, v2, 16, 1
	v_add3_u32 v1, v2, v1, s33
	v_bfe_u32 v2, v3, 16, 1
	v_add3_u32 v2, v3, v2, s33
	v_lshrrev_b32_e32 v1, 16, v1
	v_and_or_b32 v1, v2, s29, v1
	global_store_dwordx2 v[16:17], v[0:1], off offset:1632

.LBB0_247:
	s_or_b64 exec, exec, s[2:3]
	v_and_b32_e32 v33, 64, v229
	v_xor_b32_e32 v32, 16, v229
	v_add_u32_e32 v33, 64, v33
	v_cmp_lt_i32_e32 vcc, v32, v33
	v_mul_f32_e32 v37, 0x3e000000, v37
	v_mul_f32_e32 v38, 0x3e000000, v38
	v_cndmask_b32_e32 v34, v229, v32, vcc
	v_xor_b32_e32 v32, 32, v229
	v_cmp_lt_i32_e32 vcc, v32, v33
	v_lshlrev_b32_e32 v47, 2, v34
	v_mul_f32_e32 v34, 0x3e000000, v36
	v_cndmask_b32_e32 v33, v229, v32, vcc
	v_lshlrev_b32_e32 v32, 2, v48
	v_cmp_gt_i32_e32 vcc, v32, v40
	v_lshlrev_b32_e32 v46, 2, v33
	v_sub_u32_e32 v33, v44, v49
	v_cndmask_b32_e32 v34, v230, v34, vcc
	v_cmp_ge_i32_e32 vcc, v32, v40
	v_or_b32_e32 v44, 2, v32
	s_waitcnt vmcnt(0)
	v_max_f32_e32 v36, v43, v43
	v_cndmask_b32_e32 v37, v230, v37, vcc
	v_cmp_gt_i32_e32 vcc, v44, v40
	v_or_b32_e32 v44, 3, v32
	v_mul_f32_e32 v39, 0x3e000000, v39
	v_cndmask_b32_e32 v38, v230, v38, vcc
	v_cmp_gt_i32_e32 vcc, v44, v40
	v_or_b32_e32 v49, 16, v32
	v_max_f32_e32 v36, v36, v34
	v_cndmask_b32_e32 v39, v230, v39, vcc
	v_cmp_gt_i32_e32 vcc, v49, v40
	v_mul_f32_e32 v28, 0x3e000000, v28
	v_max3_f32 v36, v36, v37, v38
	v_cndmask_b32_e32 v49, v230, v28, vcc
	v_max3_f32 v28, v36, v39, v49
	v_or_b32_e32 v36, 17, v32
	v_cmp_gt_i32_e32 vcc, v36, v40
	v_mul_f32_e32 v29, 0x3e000000, v29
	v_mul_f32_e32 v24, 0x3e000000, v24
	v_cndmask_b32_e32 v50, v230, v29, vcc
	v_or_b32_e32 v29, 18, v32
	v_cmp_gt_i32_e32 vcc, v29, v40
	v_mul_f32_e32 v29, 0x3e000000, v30
	v_mul_f32_e32 v25, 0x3e000000, v25
	v_cndmask_b32_e32 v51, v230, v29, vcc
	v_or_b32_e32 v29, 19, v32
	v_cmp_gt_i32_e32 vcc, v29, v40
	v_mul_f32_e32 v29, 0x3e000000, v31
	v_mul_f32_e32 v26, 0x3e000000, v26
	v_cndmask_b32_e32 v52, v230, v29, vcc
	v_or_b32_e32 v29, 32, v32
	v_cmp_gt_i32_e32 vcc, v29, v40
	v_or_b32_e32 v29, 33, v32
	v_mul_f32_e32 v27, 0x3e000000, v27
	v_cndmask_b32_e32 v24, v230, v24, vcc
	v_cmp_gt_i32_e32 vcc, v29, v40
	v_or_b32_e32 v29, 34, v32
	v_mul_f32_e32 v20, 0x3e000000, v20
	v_cndmask_b32_e32 v25, v230, v25, vcc
	v_cmp_gt_i32_e32 vcc, v29, v40
	v_or_b32_e32 v29, 35, v32
	v_max3_f32 v28, v28, v50, v51
	v_cndmask_b32_e32 v26, v230, v26, vcc
	v_cmp_gt_i32_e32 vcc, v29, v40
	v_or_b32_e32 v29, 48, v32
	v_mul_f32_e32 v21, 0x3e000000, v21
	v_cndmask_b32_e32 v27, v230, v27, vcc
	v_cmp_gt_i32_e32 vcc, v29, v40
	v_or_b32_e32 v29, 49, v32
	v_max3_f32 v28, v28, v52, v24
	v_cndmask_b32_e32 v20, v230, v20, vcc
	v_cmp_gt_i32_e32 vcc, v29, v40
	v_or_b32_e32 v29, 50, v32
	v_mul_f32_e32 v22, 0x3e000000, v22
	v_cndmask_b32_e32 v21, v230, v21, vcc
	v_cmp_gt_i32_e32 vcc, v29, v40
	v_or_b32_e32 v29, 51, v32
	v_max3_f32 v28, v28, v25, v26
	v_cndmask_b32_e32 v22, v230, v22, vcc
	v_cmp_gt_i32_e32 vcc, v29, v40
	v_mul_f32_e32 v23, 0x3e000000, v23
	v_or_b32_e32 v29, 64, v32
	v_max3_f32 v28, v28, v27, v20
	v_cndmask_b32_e32 v23, v230, v23, vcc
	v_cmp_gt_i32_e32 vcc, v29, v40
	v_mul_f32_e32 v16, 0x3e000000, v16
	v_max3_f32 v28, v28, v21, v22
	v_cndmask_b32_e32 v53, v230, v16, vcc
	v_max3_f32 v16, v28, v23, v53
	v_or_b32_e32 v28, 0x41, v32
	v_cmp_gt_i32_e32 vcc, v28, v40
	v_mul_f32_e32 v17, 0x3e000000, v17
	v_mul_f32_e32 v12, 0x3e000000, v12
	v_cndmask_b32_e32 v54, v230, v17, vcc
	v_or_b32_e32 v17, 0x42, v32
	v_cmp_gt_i32_e32 vcc, v17, v40
	v_mul_f32_e32 v17, 0x3e000000, v18
	v_mul_f32_e32 v13, 0x3e000000, v13
	v_cndmask_b32_e32 v18, v230, v17, vcc
	v_or_b32_e32 v17, 0x43, v32
	v_cmp_gt_i32_e32 vcc, v17, v40
	v_mul_f32_e32 v17, 0x3e000000, v19
	v_max3_f32 v16, v16, v54, v18
	v_cndmask_b32_e32 v19, v230, v17, vcc
	v_or_b32_e32 v17, 0x50, v32
	v_cmp_gt_i32_e32 vcc, v17, v40
	v_mul_f32_e32 v8, 0x3e000000, v8
	v_mul_f32_e32 v9, 0x3e000000, v9
	v_cndmask_b32_e32 v55, v230, v12, vcc
	v_max3_f32 v12, v16, v19, v55
	v_or_b32_e32 v16, 0x51, v32
	v_cmp_gt_i32_e32 vcc, v16, v40
	v_mul_f32_e32 v4, 0x3e000000, v4
	v_mul_f32_e32 v5, 0x3e000000, v5
	v_cndmask_b32_e32 v56, v230, v13, vcc
	v_or_b32_e32 v13, 0x52, v32
	v_cmp_gt_i32_e32 vcc, v13, v40
	v_mul_f32_e32 v13, 0x3e000000, v14
	s_movk_i32 s2, 0x84
	v_cndmask_b32_e32 v14, v230, v13, vcc
	v_or_b32_e32 v13, 0x53, v32
	v_cmp_gt_i32_e32 vcc, v13, v40
	v_mul_f32_e32 v13, 0x3e000000, v15
	v_max3_f32 v12, v12, v56, v14
	v_cndmask_b32_e32 v15, v230, v13, vcc
	v_or_b32_e32 v13, 0x60, v32
	v_cmp_gt_i32_e32 vcc, v13, v40
	v_cmp_le_i32_e64 s[4:5], v32, v40
	v_add_u32_e32 v35, 0x80, v40
	v_cndmask_b32_e32 v57, v230, v8, vcc
	v_max3_f32 v8, v12, v15, v57
	v_or_b32_e32 v12, 0x61, v32
	v_cmp_gt_i32_e32 vcc, v12, v40
	v_mul_f32_e32 v0, 0x3e000000, v0
	v_mul_f32_e32 v1, 0x3e000000, v1
	v_cndmask_b32_e32 v58, v230, v9, vcc
	v_or_b32_e32 v9, 0x62, v32
	v_cmp_gt_i32_e32 vcc, v9, v40
	v_mul_f32_e32 v9, 0x3e000000, v10
	v_mul_f32_e32 v2, 0x3e000000, v2
	v_cndmask_b32_e32 v59, v230, v9, vcc
	v_or_b32_e32 v9, 0x63, v32
	v_cmp_gt_i32_e32 vcc, v9, v40
	v_mul_f32_e32 v9, 0x3e000000, v11
	v_max3_f32 v8, v8, v58, v59
	v_cndmask_b32_e32 v60, v230, v9, vcc
	v_or_b32_e32 v9, 0x70, v32
	v_cmp_gt_i32_e32 vcc, v9, v40
	v_mul_f32_e32 v3, 0x3e000000, v3
	s_nop 0
	v_cndmask_b32_e32 v61, v230, v4, vcc
	v_max3_f32 v4, v8, v60, v61
	v_or_b32_e32 v8, 0x71, v32
	v_cmp_gt_i32_e32 vcc, v8, v40
	s_nop 1
	v_cndmask_b32_e32 v62, v230, v5, vcc
	v_or_b32_e32 v5, 0x72, v32
	v_cmp_gt_i32_e32 vcc, v5, v40
	v_mul_f32_e32 v5, 0x3e000000, v6
	s_nop 0
	v_cndmask_b32_e32 v63, v230, v5, vcc
	v_or_b32_e32 v5, 0x73, v32
	v_cmp_gt_i32_e32 vcc, v5, v40
	v_mul_f32_e32 v5, 0x3e000000, v7
	v_max3_f32 v4, v4, v62, v63
	v_cndmask_b32_e32 v64, v230, v5, vcc
	v_or_b32_e32 v5, 0x80, v32
	v_cmp_gt_u32_e32 vcc, s2, v5
	s_and_b64 vcc, vcc, s[4:5]
	v_or_b32_e32 v5, 0x81, v32
	v_cndmask_b32_e32 v0, v230, v0, vcc
	v_cmp_gt_u32_e32 vcc, s2, v5
	v_cmp_le_i32_e64 s[4:5], v5, v35
	s_and_b64 vcc, vcc, s[4:5]
	v_or_b32_e32 v5, 0x82, v32
	v_cndmask_b32_e32 v1, v230, v1, vcc
	v_cmp_gt_u32_e32 vcc, s2, v5
	v_cmp_le_i32_e64 s[4:5], v5, v35
	s_and_b64 vcc, vcc, s[4:5]
	v_cndmask_b32_e32 v65, v230, v2, vcc
	v_cmp_eq_u32_e32 vcc, 0, v48
	v_cmp_le_i32_e64 s[4:5], v44, v40
	v_max3_f32 v4, v4, v64, v0
	s_and_b64 vcc, vcc, s[4:5]
	v_max3_f32 v2, v4, v1, v65
	v_cndmask_b32_e32 v3, v230, v3, vcc
	s_mov_b32 s2, 0xf149f2ca
	v_max3_f32 v2, v2, v3, s2
	ds_bpermute_b32 v4, v47, v2
	s_waitcnt lgkmcnt(0)
	v_max_f32_e32 v4, v4, v4
	v_max_f32_e32 v2, v2, v4
	ds_bpermute_b32 v4, v46, v2
	s_waitcnt lgkmcnt(0)
	v_max_f32_e32 v4, v4, v4
	v_max_f32_e32 v44, v2, v4
	v_sub_f32_e32 v4, v37, v44
	v_mul_f32_e32 v4, 0x3fb8aa3b, v4
	v_exp_f32_e32 v30, v4
	v_sub_f32_e32 v4, v38, v44
	v_mul_f32_e32 v4, 0x3fb8aa3b, v4
	v_exp_f32_e32 v29, v4
	v_sub_f32_e32 v4, v39, v44
	v_mul_f32_e32 v4, 0x3fb8aa3b, v4
	v_exp_f32_e32 v31, v4
	v_sub_f32_e32 v4, v49, v44
	v_mul_f32_e32 v4, 0x3fb8aa3b, v4
	v_exp_f32_e32 v36, v4
	v_sub_f32_e32 v4, v50, v44
	v_mul_f32_e32 v4, 0x3fb8aa3b, v4
	v_exp_f32_e32 v38, v4
	v_sub_f32_e32 v4, v51, v44
	v_mul_f32_e32 v4, 0x3fb8aa3b, v4
	v_exp_f32_e32 v37, v4
	v_sub_f32_e32 v4, v52, v44
	v_mul_f32_e32 v4, 0x3fb8aa3b, v4
	v_exp_f32_e32 v39, v4
	v_sub_f32_e32 v4, v24, v44
	v_mul_f32_e32 v4, 0x3fb8aa3b, v4
	v_exp_f32_e32 v12, v4
	v_sub_f32_e32 v4, v25, v44
	v_mul_f32_e32 v4, 0x3fb8aa3b, v4
	v_exp_f32_e32 v16, v4
	v_sub_f32_e32 v4, v26, v44
	v_mul_f32_e32 v4, 0x3fb8aa3b, v4
	v_exp_f32_e32 v13, v4
	v_sub_f32_e32 v4, v27, v44
	v_mul_f32_e32 v4, 0x3fb8aa3b, v4
	v_sub_f32_e32 v2, v34, v44
	v_exp_f32_e32 v17, v4
	v_sub_f32_e32 v4, v20, v44
	v_mul_f32_e32 v2, 0x3fb8aa3b, v2
	v_mul_f32_e32 v4, 0x3fb8aa3b, v4
	v_exp_f32_e32 v28, v2
	v_exp_f32_e32 v26, v4
	v_sub_f32_e32 v4, v21, v44
	v_mul_f32_e32 v4, 0x3fb8aa3b, v4
	v_exp_f32_e32 v34, v4
	v_sub_f32_e32 v4, v22, v44
	v_mul_f32_e32 v4, 0x3fb8aa3b, v4
	v_add_f32_e32 v2, 0, v28
	v_exp_f32_e32 v27, v4
	v_sub_f32_e32 v4, v23, v44
	v_add_f32_e32 v2, v30, v2
	v_mul_f32_e32 v4, 0x3fb8aa3b, v4
	v_add_f32_e32 v2, v29, v2
	v_exp_f32_e32 v35, v4
	v_sub_f32_e32 v4, v53, v44
	v_add_f32_e32 v2, v31, v2
	v_mul_f32_e32 v4, 0x3fb8aa3b, v4
	v_add_f32_e32 v2, v36, v2
	v_exp_f32_e32 v8, v4
	v_sub_f32_e32 v4, v54, v44
	v_add_f32_e32 v2, v38, v2
	v_mul_f32_e32 v4, 0x3fb8aa3b, v4
	v_add_f32_e32 v2, v37, v2
	v_exp_f32_e32 v10, v4
	v_sub_f32_e32 v4, v18, v44
	v_add_f32_e32 v2, v39, v2
	v_mul_f32_e32 v4, 0x3fb8aa3b, v4
	v_add_f32_e32 v2, v12, v2
	v_exp_f32_e32 v9, v4
	v_sub_f32_e32 v4, v19, v44
	v_add_f32_e32 v2, v16, v2
	v_mul_f32_e32 v4, 0x3fb8aa3b, v4
	v_add_f32_e32 v2, v13, v2
	v_exp_f32_e32 v11, v4
	v_sub_f32_e32 v4, v55, v44
	v_add_f32_e32 v2, v17, v2
	v_mul_f32_e32 v4, 0x3fb8aa3b, v4
	v_add_f32_e32 v2, v26, v2
	v_exp_f32_e32 v22, v4
	v_sub_f32_e32 v4, v56, v44
	v_add_f32_e32 v2, v34, v2
	v_mul_f32_e32 v4, 0x3fb8aa3b, v4
	v_add_f32_e32 v2, v27, v2
	v_exp_f32_e32 v24, v4
	v_sub_f32_e32 v4, v14, v44
	v_add_f32_e32 v2, v35, v2
	v_mul_f32_e32 v4, 0x3fb8aa3b, v4
	v_add_f32_e32 v2, v8, v2
	v_exp_f32_e32 v23, v4
	v_sub_f32_e32 v4, v15, v44
	v_add_f32_e32 v2, v10, v2
	v_mul_f32_e32 v4, 0x3fb8aa3b, v4
	v_add_f32_e32 v2, v9, v2
	v_exp_f32_e32 v25, v4
	v_sub_f32_e32 v4, v57, v44
	v_sub_f32_e32 v5, v58, v44
	v_add_f32_e32 v2, v11, v2
	v_mul_f32_e32 v4, 0x3fb8aa3b, v4
	v_mul_f32_e32 v5, 0x3fb8aa3b, v5
	v_add_f32_e32 v2, v22, v2
	v_exp_f32_e32 v4, v4
	v_exp_f32_e32 v6, v5
	v_sub_f32_e32 v5, v59, v44
	v_add_f32_e32 v2, v24, v2
	v_mul_f32_e32 v5, 0x3fb8aa3b, v5
	v_sub_f32_e32 v7, v60, v44
	v_add_f32_e32 v2, v23, v2
	v_exp_f32_e32 v5, v5
	v_mul_f32_e32 v7, 0x3fb8aa3b, v7
	v_sub_f32_e32 v14, v61, v44
	v_sub_f32_e32 v15, v62, v44
	v_add_f32_e32 v2, v25, v2
	v_exp_f32_e32 v7, v7
	v_mul_f32_e32 v14, 0x3fb8aa3b, v14
	v_mul_f32_e32 v15, 0x3fb8aa3b, v15
	v_add_f32_e32 v2, v4, v2
	v_exp_f32_e32 v14, v14
	v_exp_f32_e32 v18, v15
	v_sub_f32_e32 v15, v63, v44
	v_add_f32_e32 v2, v6, v2
	v_mul_f32_e32 v15, 0x3fb8aa3b, v15
	v_sub_f32_e32 v19, v64, v44
	v_add_f32_e32 v2, v5, v2
	v_exp_f32_e32 v15, v15
	v_mul_f32_e32 v19, 0x3fb8aa3b, v19
	v_sub_f32_e32 v0, v0, v44
	v_add_f32_e32 v2, v7, v2
	v_exp_f32_e32 v19, v19
	v_mul_f32_e32 v0, 0x3fb8aa3b, v0
	v_add_f32_e32 v2, v14, v2
	v_exp_f32_e32 v0, v0
	v_add_f32_e32 v2, v18, v2
	v_add_f32_e32 v2, v15, v2
	v_sub_f32_e32 v1, v1, v44
	v_add_f32_e32 v2, v19, v2
	v_mul_f32_e32 v1, 0x3fb8aa3b, v1
	v_add_f32_e32 v20, v0, v2
	v_exp_f32_e32 v2, v1
	v_sub_f32_e32 v1, v65, v44
	v_mul_f32_e32 v1, 0x3fb8aa3b, v1
	v_sub_f32_e32 v3, v3, v44
	v_exp_f32_e32 v1, v1
	v_mul_f32_e32 v3, 0x3fb8aa3b, v3
	v_sub_f32_e32 v21, 0xf149f2ca, v44
	v_exp_f32_e32 v3, v3
	v_mul_f32_e32 v21, 0x3fb8aa3b, v21
	v_exp_f32_e32 v21, v21
	v_add_f32_e32 v20, v2, v20
	v_add_f32_e32 v20, v1, v20
	v_add_f32_e32 v20, v3, v20
	v_add_f32_e32 v20, v21, v20
	v_add_f32_e32 v20, v21, v20
	v_add_f32_e32 v20, v21, v20
	v_add_f32_e32 v20, v21, v20
	ds_bpermute_b32 v47, v47, v20
	v_sub_f32_e32 v43, v43, v44
	v_mul_f32_e32 v43, 0x3fb8aa3b, v43
	v_exp_f32_e32 v43, v43
	s_waitcnt lgkmcnt(0)
	v_add_f32_e32 v20, v20, v47
	ds_bpermute_b32 v46, v46, v20
	s_waitcnt lgkmcnt(0)
	v_add_f32_e32 v20, v20, v46
	v_add_f32_e32 v20, v43, v20
	v_div_scale_f32 v43, s[2:3], v20, v20, 1.0
	v_rcp_f32_e32 v44, v43
	v_div_scale_f32 v46, vcc, 1.0, v20, 1.0
	s_movk_i32 s2, 0x210
	v_fma_f32 v47, -v43, v44, 1.0
	v_fmac_f32_e32 v44, v47, v44
	v_mul_f32_e32 v47, v46, v44
	v_fma_f32 v48, -v43, v47, v46
	v_fmac_f32_e32 v47, v48, v44
	v_fma_f32 v43, -v43, v47, v46
	v_div_fmas_f32 v43, v43, v44, v47
	v_div_fixup_f32 v20, v43, v20, 1.0
	v_pk_mul_f32 v[30:31], v[30:31], v[20:21] op_sel_hi:[1,0]
	v_pk_mul_f32 v[38:39], v[38:39], v[20:21] op_sel_hi:[1,0]
	v_pk_mul_f32 v[28:29], v[28:29], v[20:21] op_sel_hi:[1,0]
	v_pk_mul_f32 v[36:37], v[36:37], v[20:21] op_sel_hi:[1,0]
	v_bfe_u32 v43, v39, 16, 1
	v_bfe_u32 v44, v38, 16, 1
	v_bfe_u32 v46, v31, 16, 1
	v_bfe_u32 v47, v30, 16, 1
	v_add3_u32 v46, v31, v46, s33
	v_add3_u32 v38, v38, v44, s33
	v_add3_u32 v39, v39, v43, s33
	v_bfe_u32 v31, v29, 16, 1
	v_bfe_u32 v43, v36, 16, 1
	v_bfe_u32 v44, v37, 16, 1
	v_add3_u32 v47, v30, v47, s33
	v_bfe_u32 v30, v28, 16, 1
	v_add3_u32 v37, v37, v44, s33
	v_add3_u32 v36, v36, v43, s33
	v_add3_u32 v43, v29, v31, s33
	v_add3_u32 v44, v28, v30, s33
	v_mad_u32_u24 v33, v45, s2, v33
	v_lshrrev_b32_e32 v43, 16, v43
	v_lshrrev_b32_e32 v37, 16, v37
	v_add_u32_e32 v60, 0x9000, v33
	v_lshrrev_b32_e32 v44, 16, v44
	v_lshrrev_b32_e32 v36, 16, v36
	v_and_or_b32 v39, v39, s29, v37
	v_and_or_b32 v37, v46, s29, v43
	v_add_u32_e32 v43, 0xb000, v33
	v_add_u32_e32 v61, 0xd000, v33
	v_add_u32_e32 v33, 0xf000, v33
	ds_read2_b64 v[28:31], v60 offset1:4
	v_and_or_b32 v38, v38, s29, v36
	v_and_or_b32 v36, v47, s29, v44
	ds_read2_b64 v[44:47], v43 offset0:32 offset1:36
	ds_read2_b64 v[48:51], v61 offset0:64 offset1:68
	ds_read2_b64 v[52:55], v33 offset0:96 offset1:100
	s_waitcnt lgkmcnt(3)
	v_mfma_f32_16x16x32_bf16 v[28:31], v[28:31], v[36:39], 0
	s_waitcnt lgkmcnt(2)
	v_mfma_f32_16x16x32_bf16 v[44:47], v[44:47], v[36:39], 0
	s_waitcnt lgkmcnt(1)
	v_mfma_f32_16x16x32_bf16 v[48:51], v[48:51], v[36:39], 0
	s_waitcnt lgkmcnt(0)
	v_mfma_f32_16x16x32_bf16 v[36:39], v[52:55], v[36:39], 0
	ds_read2_b64 v[132:135], v60 offset0:8 offset1:12
	ds_read2_b64 v[136:139], v43 offset0:40 offset1:44
	ds_read2_b64 v[140:143], v61 offset0:72 offset1:76
	ds_read2_b64 v[144:147], v33 offset0:104 offset1:108
	v_mul_f32_e64 v16, v16, v20
	v_mul_f32_e64 v17, v17, v20
	v_pk_mul_f32 v[34:35], v[34:35], v[20:21] op_sel_hi:[1,0]
	v_pk_mul_f32 v[12:13], v[12:13], v[20:21] op_sel_hi:[1,0]
	v_pk_mul_f32 v[26:27], v[26:27], v[20:21] op_sel_hi:[1,0]
	v_bfe_u32 v52, v35, 16, 1
	v_bfe_u32 v53, v34, 16, 1
	v_bfe_u32 v54, v17, 16, 1
	v_bfe_u32 v55, v16, 16, 1
	v_add3_u32 v16, v16, v55, s33
	v_add3_u32 v17, v17, v54, s33
	v_add3_u32 v34, v34, v53, s33
	v_add3_u32 v35, v35, v52, s33
	v_bfe_u32 v52, v12, 16, 1
	v_bfe_u32 v53, v13, 16, 1
	v_bfe_u32 v54, v26, 16, 1
	v_bfe_u32 v55, v27, 16, 1
	v_add3_u32 v27, v27, v55, s33
	v_add3_u32 v26, v26, v54, s33
	v_add3_u32 v13, v13, v53, s33
	v_add3_u32 v12, v12, v52, s33
	v_lshrrev_b32_e32 v12, 16, v12
	v_lshrrev_b32_e32 v13, 16, v13
	v_lshrrev_b32_e32 v26, 16, v26
	v_lshrrev_b32_e32 v27, 16, v27
	v_and_or_b32 v59, v35, s29, v27
	v_and_or_b32 v58, v34, s29, v26
	v_and_or_b32 v57, v17, s29, v13
	v_and_or_b32 v56, v16, s29, v12
	s_waitcnt lgkmcnt(3)
	s_nop 1
	v_mfma_f32_16x16x32_bf16 v[26:29], v[132:135], v[56:59], v[28:31]
	s_waitcnt lgkmcnt(2)
	v_mfma_f32_16x16x32_bf16 v[44:47], v[136:139], v[56:59], v[44:47]
	s_waitcnt lgkmcnt(1)
	v_mfma_f32_16x16x32_bf16 v[48:51], v[140:143], v[56:59], v[48:51]
	s_waitcnt lgkmcnt(0)
	v_mfma_f32_16x16x32_bf16 v[34:37], v[144:147], v[56:59], v[36:39]
	ds_read2_b64 v[116:119], v60 offset0:16 offset1:20
	ds_read2_b64 v[120:123], v43 offset0:48 offset1:52
	ds_read2_b64 v[124:127], v61 offset0:80 offset1:84
	ds_read2_b64 v[128:131], v33 offset0:112 offset1:116
	v_mul_f32_e64 v10, v10, v20
	v_mul_f32_e64 v11, v11, v20
	v_pk_mul_f32 v[16:17], v[24:25], v[20:21] op_sel_hi:[1,0]
	v_pk_mul_f32 v[8:9], v[8:9], v[20:21] op_sel_hi:[1,0]
	v_pk_mul_f32 v[12:13], v[22:23], v[20:21] op_sel_hi:[1,0]
	v_bfe_u32 v22, v17, 16, 1
	v_bfe_u32 v23, v16, 16, 1
	v_bfe_u32 v24, v11, 16, 1
	v_bfe_u32 v25, v10, 16, 1
	v_add3_u32 v30, v10, v25, s33
	v_add3_u32 v31, v11, v24, s33
	v_add3_u32 v16, v16, v23, s33
	v_add3_u32 v17, v17, v22, s33
	v_bfe_u32 v10, v8, 16, 1
	v_bfe_u32 v11, v9, 16, 1
	v_bfe_u32 v22, v12, 16, 1
	v_bfe_u32 v23, v13, 16, 1
	v_add3_u32 v13, v13, v23, s33
	v_add3_u32 v12, v12, v22, s33
	v_add3_u32 v22, v9, v11, s33
	v_add3_u32 v23, v8, v10, s33
	v_lshrrev_b32_e32 v38, 16, v23
	v_lshrrev_b32_e32 v22, 16, v22
	v_lshrrev_b32_e32 v12, 16, v12
	v_lshrrev_b32_e32 v13, 16, v13
	v_and_or_b32 v25, v17, s29, v13
	v_and_or_b32 v24, v16, s29, v12
	v_and_or_b32 v23, v31, s29, v22
	v_and_or_b32 v22, v30, s29, v38
	s_waitcnt lgkmcnt(3)
	s_nop 1
	v_mfma_f32_16x16x32_bf16 v[8:11], v[116:119], v[22:25], v[26:29]
	s_waitcnt lgkmcnt(2)
	v_mfma_f32_16x16x32_bf16 v[26:29], v[120:123], v[22:25], v[44:47]
	s_waitcnt lgkmcnt(1)
	v_mfma_f32_16x16x32_bf16 v[44:47], v[124:127], v[22:25], v[48:51]
	s_waitcnt lgkmcnt(0)
	v_mfma_f32_16x16x32_bf16 v[22:25], v[128:131], v[22:25], v[34:37]
	ds_read2_b64 v[132:135], v60 offset0:24 offset1:28
	ds_read2_b64 v[136:139], v43 offset0:56 offset1:60
	ds_read2_b64 v[140:143], v61 offset0:88 offset1:92
	ds_read2_b64 v[144:147], v33 offset0:120 offset1:124
	v_mul_f32_e64 v6, v6, v20
	v_mul_f32_e64 v7, v7, v20
	v_pk_mul_f32 v[12:13], v[14:15], v[20:21] op_sel_hi:[1,0]
	v_pk_mul_f32 v[14:15], v[18:19], v[20:21] op_sel_hi:[1,0]
	v_pk_mul_f32 v[4:5], v[4:5], v[20:21] op_sel_hi:[1,0]
	v_bfe_u32 v16, v15, 16, 1
	v_bfe_u32 v17, v14, 16, 1
	v_bfe_u32 v18, v7, 16, 1
	v_bfe_u32 v19, v6, 16, 1
	v_add3_u32 v19, v6, v19, s33
	v_add3_u32 v18, v7, v18, s33
	v_add3_u32 v14, v14, v17, s33
	v_add3_u32 v15, v15, v16, s33
	v_bfe_u32 v6, v4, 16, 1
	v_bfe_u32 v7, v5, 16, 1
	v_bfe_u32 v16, v12, 16, 1
	v_bfe_u32 v17, v13, 16, 1
	v_add3_u32 v13, v13, v17, s33
	v_add3_u32 v12, v12, v16, s33
	v_add3_u32 v16, v5, v7, s33
	v_add3_u32 v17, v4, v6, s33
	v_lshrrev_b32_e32 v17, 16, v17
	v_lshrrev_b32_e32 v16, 16, v16
	v_lshrrev_b32_e32 v12, 16, v12
	v_lshrrev_b32_e32 v13, 16, v13
	v_and_or_b32 v15, v15, s29, v13
	v_and_or_b32 v14, v14, s29, v12
	v_and_or_b32 v13, v18, s29, v16
	v_and_or_b32 v12, v19, s29, v17
	s_waitcnt lgkmcnt(3)
	s_nop 1
	v_mfma_f32_16x16x32_bf16 v[4:7], v[132:135], v[12:15], v[8:11]
	s_waitcnt lgkmcnt(2)
	v_mfma_f32_16x16x32_bf16 v[8:11], v[136:139], v[12:15], v[26:29]
	s_waitcnt lgkmcnt(1)
	v_mfma_f32_16x16x32_bf16 v[16:19], v[140:143], v[12:15], v[44:47]
	s_waitcnt lgkmcnt(0)
	v_mfma_f32_16x16x32_bf16 v[22:25], v[144:147], v[12:15], v[22:25]
	ds_read2_b64 v[116:119], v60 offset0:32 offset1:36
	ds_read2_b64 v[120:123], v43 offset0:64 offset1:68
	ds_read2_b64 v[124:127], v61 offset0:96 offset1:100
	ds_read2_b64 v[128:131], v33 offset0:128 offset1:132
	v_mul_f32_e64 v0, v0, v20
	v_mul_f32_e64 v1, v1, v20
	v_pk_mul_f32 v[2:3], v[2:3], v[20:21] op_sel_hi:[1,0]
	v_and_b32_sdwa v12, v1, v228 dst_sel:DWORD dst_unused:UNUSED_PAD src0_sel:WORD_1 src1_sel:DWORD
	v_and_b32_sdwa v13, v0, v228 dst_sel:DWORD dst_unused:UNUSED_PAD src0_sel:WORD_1 src1_sel:DWORD
	v_add3_u32 v13, v0, v13, s33
	v_add3_u32 v12, v1, v12, s33
	v_and_b32_sdwa v0, v3, v228 dst_sel:DWORD dst_unused:UNUSED_PAD src0_sel:WORD_1 src1_sel:DWORD
	v_and_b32_sdwa v1, v2, v228 dst_sel:DWORD dst_unused:UNUSED_PAD src0_sel:WORD_1 src1_sel:DWORD
	v_add3_u32 v0, v3, v0, s33
	v_add3_u32 v1, v2, v1, s33
	v_and_b32_e32 v14, 0xffff0000, v0
	v_and_b32_e32 v15, 0xffff0000, v1
	v_or_b32_sdwa v27, v14, v12 dst_sel:DWORD dst_unused:UNUSED_PAD src0_sel:DWORD src1_sel:WORD_1
	v_mul_f32_e32 v12, v21, v20
	v_or_b32_sdwa v26, v15, v13 dst_sel:DWORD dst_unused:UNUSED_PAD src0_sel:DWORD src1_sel:WORD_1
	v_bfe_u32 v13, v12, 16, 1
	v_add3_u32 v12, v12, v13, s33
	v_lshrrev_b32_e32 v13, 16, v12
	v_and_or_b32 v28, v12, s29, v13
	v_mov_b32_e32 v29, v28
	s_waitcnt lgkmcnt(3)
	s_nop 1
	v_mfma_f32_16x16x32_bf16 v[12:15], v[116:119], v[26:29], v[4:7]
	s_waitcnt lgkmcnt(2)
	v_mfma_f32_16x16x32_bf16 v[8:11], v[120:123], v[26:29], v[8:11]
	s_waitcnt lgkmcnt(1)
	v_mfma_f32_16x16x32_bf16 v[4:7], v[124:127], v[26:29], v[16:19]
	s_waitcnt lgkmcnt(0)
	v_mfma_f32_16x16x32_bf16 v[0:3], v[128:131], v[26:29], v[22:25]
	s_and_b64 exec, exec, s[0:1]
	s_cbranch_execz .LBB0_249
	s_lshl_b32 s0, s17, 11
	s_add_u32 s0, s10, s0
	v_lshlrev_b64 v[16:17], 11, v[40:41]
	s_addc_u32 s1, s11, 0
	v_add_lshl_u32 v18, v42, s18, 6
	v_lshl_add_u64 v[16:17], s[0:1], 0, v[16:17]
	v_ashrrev_i32_e32 v19, 31, v18
	v_lshl_add_u64 v[16:17], v[18:19], 1, v[16:17]
	v_bfe_u32 v18, v12, 16, 1
	v_add3_u32 v12, v12, v18, s33
	v_bfe_u32 v18, v13, 16, 1
	v_add3_u32 v13, v13, v18, s33
	v_lshrrev_b32_e32 v12, 16, v12
	v_and_or_b32 v12, v13, s29, v12
	v_bfe_u32 v13, v14, 16, 1
	v_add3_u32 v13, v14, v13, s33
	v_bfe_u32 v14, v15, 16, 1
	v_mov_b32_e32 v33, v80
	v_add3_u32 v14, v15, v14, s33
	v_lshrrev_b32_e32 v13, 16, v13
	v_lshl_add_u64 v[16:17], v[32:33], 1, v[16:17]
	v_and_or_b32 v13, v14, s29, v13
	global_store_dwordx2 v[16:17], v[12:13], off
	v_bfe_u32 v12, v8, 16, 1
	v_add3_u32 v8, v8, v12, s33
	v_bfe_u32 v12, v9, 16, 1
	v_add3_u32 v9, v9, v12, s33
	v_lshrrev_b32_e32 v8, 16, v8
	v_and_or_b32 v8, v9, s29, v8
	v_bfe_u32 v9, v10, 16, 1
	v_add3_u32 v9, v10, v9, s33
	v_bfe_u32 v10, v11, 16, 1
	v_add3_u32 v10, v11, v10, s33
	v_lshrrev_b32_e32 v9, 16, v9
	v_and_or_b32 v9, v10, s29, v9
	global_store_dwordx2 v[16:17], v[8:9], off offset:32
	v_bfe_u32 v8, v4, 16, 1
	v_add3_u32 v4, v4, v8, s33
	v_bfe_u32 v8, v5, 16, 1
	v_add3_u32 v5, v5, v8, s33
	v_lshrrev_b32_e32 v4, 16, v4
	v_and_or_b32 v4, v5, s29, v4
	v_bfe_u32 v5, v6, 16, 1
	v_add3_u32 v5, v6, v5, s33
	v_bfe_u32 v6, v7, 16, 1
	v_add3_u32 v6, v7, v6, s33
	v_lshrrev_b32_e32 v5, 16, v5
	v_and_or_b32 v5, v6, s29, v5
	global_store_dwordx2 v[16:17], v[4:5], off offset:64
	v_bfe_u32 v4, v0, 16, 1
	v_add3_u32 v0, v0, v4, s33
	v_bfe_u32 v4, v1, 16, 1
	v_add3_u32 v1, v1, v4, s33
	v_lshrrev_b32_e32 v0, 16, v0
	v_and_or_b32 v0, v1, s29, v0
	v_bfe_u32 v1, v2, 16, 1
	v_add3_u32 v1, v2, v1, s33
	v_bfe_u32 v2, v3, 16, 1
	v_add3_u32 v2, v3, v2, s33
	v_lshrrev_b32_e32 v1, 16, v1
	v_and_or_b32 v1, v2, s29, v1
	global_store_dwordx2 v[16:17], v[0:1], off offset:96

.LBB0_256:
	ds_read_b128 v[116:119], v82
	ds_read_b128 v[120:123], v82 offset:64
	ds_read_b128 v[124:127], v82 offset:2304
	ds_read_b128 v[128:131], v82 offset:2368
	ds_read_b128 v[132:135], v82 offset:4608
	ds_read_b128 v[136:139], v82 offset:4672
	ds_read_b128 v[140:143], v82 offset:6912
	ds_read_b128 v[144:147], v82 offset:6976
	ds_read_b128 v[148:151], v82 offset:9216
	ds_read_b128 v[152:155], v82 offset:9280
	ds_read_b128 v[156:159], v82 offset:11520
	ds_read_b128 v[160:163], v82 offset:11584
	s_waitcnt lgkmcnt(6)
	v_mfma_f32_16x16x32_bf16 v[68:71], v[116:119], v[72:75], 0
	v_mfma_f32_16x16x32_bf16 v[64:67], v[124:127], v[72:75], 0
	v_mfma_f32_16x16x32_bf16 v[60:63], v[132:135], v[72:75], 0
	v_mfma_f32_16x16x32_bf16 v[68:71], v[120:123], v[8:11], v[68:71]
	v_mfma_f32_16x16x32_bf16 v[64:67], v[128:131], v[8:11], v[64:67]
	v_mfma_f32_16x16x32_bf16 v[60:63], v[136:139], v[8:11], v[60:63]
	ds_read_b128 v[116:119], v82 offset:13824
	ds_read_b128 v[120:123], v82 offset:13888
	ds_read_b128 v[124:127], v82 offset:16128
	ds_read_b128 v[128:131], v82 offset:16192
	ds_read_b128 v[132:135], v82 offset:18432
	ds_read_b128 v[136:139], v82 offset:18496
	s_waitcnt lgkmcnt(6)
	v_mfma_f32_16x16x32_bf16 v[56:59], v[140:143], v[72:75], 0
	v_mfma_f32_16x16x32_bf16 v[52:55], v[148:151], v[72:75], 0
	v_mfma_f32_16x16x32_bf16 v[48:51], v[156:159], v[72:75], 0
	v_mfma_f32_16x16x32_bf16 v[56:59], v[144:147], v[8:11], v[56:59]
	v_mfma_f32_16x16x32_bf16 v[52:55], v[152:155], v[8:11], v[52:55]
	v_mfma_f32_16x16x32_bf16 v[48:51], v[160:163], v[8:11], v[48:51]
	ds_read_b128 v[140:143], v82 offset:20736
	ds_read_b128 v[144:147], v82 offset:20800
	ds_read_b128 v[148:151], v82 offset:23040
	ds_read_b128 v[152:155], v82 offset:23104
	ds_read_b128 v[156:159], v82 offset:25344
	ds_read_b128 v[160:163], v82 offset:25408
	s_waitcnt lgkmcnt(6)
	v_mfma_f32_16x16x32_bf16 v[44:47], v[116:119], v[72:75], 0
	v_mfma_f32_16x16x32_bf16 v[40:43], v[124:127], v[72:75], 0
	v_mfma_f32_16x16x32_bf16 v[36:39], v[132:135], v[72:75], 0
	v_mfma_f32_16x16x32_bf16 v[44:47], v[120:123], v[8:11], v[44:47]
	v_mfma_f32_16x16x32_bf16 v[40:43], v[128:131], v[8:11], v[40:43]
	v_mfma_f32_16x16x32_bf16 v[36:39], v[136:139], v[8:11], v[36:39]
	ds_read_b128 v[116:119], v82 offset:27648
	ds_read_b128 v[120:123], v82 offset:27712
	ds_read_b128 v[124:127], v82 offset:29952
	ds_read_b128 v[128:131], v82 offset:30016
	ds_read_b128 v[132:135], v82 offset:32256
	ds_read_b128 v[136:139], v82 offset:32320
	s_waitcnt lgkmcnt(6)
	v_mfma_f32_16x16x32_bf16 v[32:35], v[140:143], v[72:75], 0
	v_mfma_f32_16x16x32_bf16 v[28:31], v[148:151], v[72:75], 0
	v_mfma_f32_16x16x32_bf16 v[24:27], v[156:159], v[72:75], 0
	v_mfma_f32_16x16x32_bf16 v[32:35], v[144:147], v[8:11], v[32:35]
	v_mfma_f32_16x16x32_bf16 v[28:31], v[152:155], v[8:11], v[28:31]
	v_mfma_f32_16x16x32_bf16 v[24:27], v[160:163], v[8:11], v[24:27]
	s_waitcnt lgkmcnt(0)
	v_mfma_f32_16x16x32_bf16 v[20:23], v[116:119], v[72:75], 0
	v_mfma_f32_16x16x32_bf16 v[16:19], v[124:127], v[72:75], 0
	v_mfma_f32_16x16x32_bf16 v[12:15], v[132:135], v[72:75], 0
	v_mfma_f32_16x16x32_bf16 v[20:23], v[120:123], v[8:11], v[20:23]
	v_mfma_f32_16x16x32_bf16 v[16:19], v[128:131], v[8:11], v[16:19]
	v_mfma_f32_16x16x32_bf16 v[12:15], v[136:139], v[8:11], v[12:15]
	ds_read_b128 v[116:119], v82 offset:34560
	ds_read_b128 v[120:123], v82 offset:34624
	s_waitcnt lgkmcnt(0)
	v_mfma_f32_16x16x32_bf16 v[124:127], v[116:119], v[72:75], 0
	v_mfma_f32_16x16x32_bf16 v[8:11], v[120:123], v[8:11], v[124:127]
	s_nop 4
	v_mul_f32_e32 v72, 0x3e000000, v68
	v_mul_f32_e32 v73, 0x3e000000, v69
	s_mov_b32 s2, 0xff61b1e6
	v_max3_f32 v72, v72, s2, v73
	v_mul_f32_e32 v73, 0x3e000000, v70
	v_mul_f32_e32 v74, 0x3e000000, v71
	v_max3_f32 v72, v72, v73, v74
	v_mul_f32_e32 v73, 0x3e000000, v64
	v_mul_f32_e32 v74, 0x3e000000, v65
	v_max3_f32 v72, v72, v73, v74
	v_mul_f32_e32 v73, 0x3e000000, v66
	v_mul_f32_e32 v74, 0x3e000000, v67
	v_max3_f32 v72, v72, v73, v74
	v_mul_f32_e32 v73, 0x3e000000, v60
	v_mul_f32_e32 v74, 0x3e000000, v61
	v_max3_f32 v72, v72, v73, v74
	v_mul_f32_e32 v73, 0x3e000000, v62
	v_mul_f32_e32 v74, 0x3e000000, v63
	v_max3_f32 v72, v72, v73, v74
	v_mul_f32_e32 v73, 0x3e000000, v56
	v_mul_f32_e32 v74, 0x3e000000, v57
	v_max3_f32 v72, v72, v73, v74
	v_mul_f32_e32 v73, 0x3e000000, v58
	v_mul_f32_e32 v74, 0x3e000000, v59
	v_max3_f32 v72, v72, v73, v74
	v_mul_f32_e32 v73, 0x3e000000, v52
	v_mul_f32_e32 v74, 0x3e000000, v53
	v_max3_f32 v72, v72, v73, v74
	v_mul_f32_e32 v73, 0x3e000000, v54
	v_mul_f32_e32 v74, 0x3e000000, v55
	v_max3_f32 v72, v72, v73, v74
	v_mul_f32_e32 v73, 0x3e000000, v48
	v_mul_f32_e32 v74, 0x3e000000, v49
	v_max3_f32 v72, v72, v73, v74
	v_mul_f32_e32 v73, 0x3e000000, v50
	v_mul_f32_e32 v74, 0x3e000000, v51
	v_max3_f32 v72, v72, v73, v74
	v_mul_f32_e32 v73, 0x3e000000, v44
	v_mul_f32_e32 v74, 0x3e000000, v45
	v_max3_f32 v72, v72, v73, v74
	v_mul_f32_e32 v73, 0x3e000000, v46
	v_mul_f32_e32 v74, 0x3e000000, v47
	v_max3_f32 v72, v72, v73, v74
	v_mul_f32_e32 v73, 0x3e000000, v40
	v_mul_f32_e32 v74, 0x3e000000, v41
	v_max3_f32 v72, v72, v73, v74
	v_mul_f32_e32 v73, 0x3e000000, v42
	v_mul_f32_e32 v74, 0x3e000000, v43
	v_max3_f32 v72, v72, v73, v74
	v_mul_f32_e32 v73, 0x3e000000, v36
	v_mul_f32_e32 v74, 0x3e000000, v37
	v_max3_f32 v72, v72, v73, v74
	v_mul_f32_e32 v73, 0x3e000000, v38
	v_mul_f32_e32 v74, 0x3e000000, v39
	v_max3_f32 v72, v72, v73, v74
	v_mul_f32_e32 v73, 0x3e000000, v32
	v_mul_f32_e32 v74, 0x3e000000, v33
	v_max3_f32 v72, v72, v73, v74
	v_mul_f32_e32 v73, 0x3e000000, v34
	v_mul_f32_e32 v74, 0x3e000000, v35
	v_max3_f32 v72, v72, v73, v74
	v_mul_f32_e32 v73, 0x3e000000, v28
	v_mul_f32_e32 v74, 0x3e000000, v29
	v_max3_f32 v72, v72, v73, v74
	v_mul_f32_e32 v73, 0x3e000000, v30
	v_mul_f32_e32 v74, 0x3e000000, v31
	v_max3_f32 v72, v72, v73, v74
	v_mul_f32_e32 v73, 0x3e000000, v24
	v_mul_f32_e32 v74, 0x3e000000, v25
	v_max3_f32 v72, v72, v73, v74
	v_mul_f32_e32 v73, 0x3e000000, v26
	v_mul_f32_e32 v74, 0x3e000000, v27
	v_max3_f32 v72, v72, v73, v74
	v_mul_f32_e32 v73, 0x3e000000, v20
	v_mul_f32_e32 v74, 0x3e000000, v21
	v_max3_f32 v72, v72, v73, v74
	v_mul_f32_e32 v73, 0x3e000000, v22
	v_mul_f32_e32 v74, 0x3e000000, v23
	v_max3_f32 v72, v72, v73, v74
	v_mul_f32_e32 v73, 0x3e000000, v16
	v_mul_f32_e32 v74, 0x3e000000, v17
	v_max3_f32 v72, v72, v73, v74
	v_mul_f32_e32 v73, 0x3e000000, v18
	v_mul_f32_e32 v74, 0x3e000000, v19
	v_max3_f32 v72, v72, v73, v74
	v_mul_f32_e32 v73, 0x3e000000, v12
	v_mul_f32_e32 v74, 0x3e000000, v13
	v_max3_f32 v72, v72, v73, v74
	v_mul_f32_e32 v73, 0x3e000000, v14
	v_mul_f32_e32 v74, 0x3e000000, v15
	v_max3_f32 v72, v72, v73, v74
	v_mul_f32_e32 v73, 0x3e000000, v8
	v_mul_f32_e32 v74, 0x3e000000, v9
	v_max3_f32 v72, v72, v73, v74
	v_mul_f32_e32 v73, 0x3e000000, v10
	v_mul_f32_e32 v74, 0x3e000000, v11
	v_max3_f32 v72, v72, v73, v74
	ds_bpermute_b32 v73, v83, v72
	s_mov_b32 s2, 0x3e000000
	s_waitcnt lgkmcnt(0)
	v_max_f32_e32 v73, v73, v73
	v_max_f32_e32 v72, v72, v73
	ds_bpermute_b32 v73, v84, v72
	s_waitcnt lgkmcnt(0)
	v_max_f32_e32 v73, v73, v73
	v_max_f32_e32 v86, v72, v73
	v_fma_f32 v68, v68, s2, -v86
	v_fma_f32 v69, v69, s2, -v86
	v_mul_f32_e32 v68, 0x3fb8aa3b, v68
	v_mul_f32_e32 v69, 0x3fb8aa3b, v69
	v_exp_f32_e32 v68, v68
	v_exp_f32_e32 v72, v69
	v_fma_f32 v69, v70, s2, -v86
	v_mul_f32_e32 v69, 0x3fb8aa3b, v69
	v_fma_f32 v70, v71, s2, -v86
	v_exp_f32_e32 v69, v69
	v_mul_f32_e32 v70, 0x3fb8aa3b, v70
	v_exp_f32_e32 v73, v70
	v_add_f32_e32 v70, 0, v68
	v_add_f32_e32 v70, v72, v70
	v_fma_f32 v64, v64, s2, -v86
	v_add_f32_e32 v70, v69, v70
	v_mul_f32_e32 v64, 0x3fb8aa3b, v64
	v_add_f32_e32 v87, v73, v70
	v_exp_f32_e32 v70, v64
	v_fma_f32 v64, v65, s2, -v86
	v_mul_f32_e32 v64, 0x3fb8aa3b, v64
	v_exp_f32_e32 v74, v64
	v_fma_f32 v64, v66, s2, -v86
	v_mul_f32_e32 v64, 0x3fb8aa3b, v64
	v_exp_f32_e32 v71, v64
	v_fma_f32 v64, v67, s2, -v86
	v_mul_f32_e32 v64, 0x3fb8aa3b, v64
	v_exp_f32_e32 v75, v64
	v_add_f32_e32 v64, v70, v87
	v_add_f32_e32 v64, v74, v64
	v_fma_f32 v60, v60, s2, -v86
	v_fma_f32 v61, v61, s2, -v86
	v_add_f32_e32 v64, v71, v64
	v_mul_f32_e32 v60, 0x3fb8aa3b, v60
	v_mul_f32_e32 v61, 0x3fb8aa3b, v61
	v_add_f32_e32 v66, v75, v64
	v_exp_f32_e32 v60, v60
	v_exp_f32_e32 v64, v61
	v_fma_f32 v61, v62, s2, -v86
	v_mul_f32_e32 v61, 0x3fb8aa3b, v61
	v_fma_f32 v62, v63, s2, -v86
	v_exp_f32_e32 v61, v61
	v_mul_f32_e32 v62, 0x3fb8aa3b, v62
	v_exp_f32_e32 v65, v62
	v_add_f32_e32 v62, v60, v66
	v_add_f32_e32 v62, v64, v62
	v_fma_f32 v56, v56, s2, -v86
	v_add_f32_e32 v62, v61, v62
	v_mul_f32_e32 v56, 0x3fb8aa3b, v56
	v_add_f32_e32 v87, v65, v62
	v_exp_f32_e32 v62, v56
	v_fma_f32 v56, v57, s2, -v86
	v_mul_f32_e32 v56, 0x3fb8aa3b, v56
	v_exp_f32_e32 v66, v56
	v_fma_f32 v56, v58, s2, -v86
	v_mul_f32_e32 v56, 0x3fb8aa3b, v56
	v_exp_f32_e32 v63, v56
	v_fma_f32 v56, v59, s2, -v86
	v_mul_f32_e32 v56, 0x3fb8aa3b, v56
	v_exp_f32_e32 v67, v56
	v_add_f32_e32 v56, v62, v87
	v_add_f32_e32 v56, v66, v56
	v_fma_f32 v52, v52, s2, -v86
	v_fma_f32 v53, v53, s2, -v86
	v_add_f32_e32 v56, v63, v56
	v_mul_f32_e32 v52, 0x3fb8aa3b, v52
	v_mul_f32_e32 v53, 0x3fb8aa3b, v53
	v_add_f32_e32 v58, v67, v56
	v_exp_f32_e32 v52, v52
	v_exp_f32_e32 v56, v53
	v_fma_f32 v53, v54, s2, -v86
	v_mul_f32_e32 v53, 0x3fb8aa3b, v53
	v_fma_f32 v54, v55, s2, -v86
	v_exp_f32_e32 v53, v53
	v_mul_f32_e32 v54, 0x3fb8aa3b, v54
	v_exp_f32_e32 v57, v54
	v_add_f32_e32 v54, v52, v58
	v_add_f32_e32 v54, v56, v54
	v_fma_f32 v48, v48, s2, -v86
	v_add_f32_e32 v54, v53, v54
	v_mul_f32_e32 v48, 0x3fb8aa3b, v48
	v_add_f32_e32 v87, v57, v54
	v_exp_f32_e32 v54, v48
	v_fma_f32 v48, v49, s2, -v86
	v_mul_f32_e32 v48, 0x3fb8aa3b, v48
	v_exp_f32_e32 v58, v48
	v_fma_f32 v48, v50, s2, -v86
	v_mul_f32_e32 v48, 0x3fb8aa3b, v48
	v_exp_f32_e32 v55, v48
	v_fma_f32 v48, v51, s2, -v86
	v_mul_f32_e32 v48, 0x3fb8aa3b, v48
	v_exp_f32_e32 v59, v48
	v_add_f32_e32 v48, v54, v87
	v_add_f32_e32 v48, v58, v48
	v_fma_f32 v44, v44, s2, -v86
	v_fma_f32 v45, v45, s2, -v86
	v_add_f32_e32 v48, v55, v48
	v_mul_f32_e32 v44, 0x3fb8aa3b, v44
	v_mul_f32_e32 v45, 0x3fb8aa3b, v45
	v_add_f32_e32 v50, v59, v48
	v_exp_f32_e32 v44, v44
	v_exp_f32_e32 v48, v45
	v_fma_f32 v45, v46, s2, -v86
	v_mul_f32_e32 v45, 0x3fb8aa3b, v45
	v_fma_f32 v46, v47, s2, -v86
	v_exp_f32_e32 v45, v45
	v_mul_f32_e32 v46, 0x3fb8aa3b, v46
	v_exp_f32_e32 v49, v46
	v_add_f32_e32 v46, v44, v50
	v_add_f32_e32 v46, v48, v46
	v_fma_f32 v40, v40, s2, -v86
	v_add_f32_e32 v46, v45, v46
	v_mul_f32_e32 v40, 0x3fb8aa3b, v40
	v_add_f32_e32 v87, v49, v46
	v_exp_f32_e32 v46, v40
	v_fma_f32 v40, v41, s2, -v86
	v_mul_f32_e32 v40, 0x3fb8aa3b, v40
	v_exp_f32_e32 v50, v40
	v_fma_f32 v40, v42, s2, -v86
	v_mul_f32_e32 v40, 0x3fb8aa3b, v40
	v_exp_f32_e32 v47, v40
	v_fma_f32 v40, v43, s2, -v86
	v_mul_f32_e32 v40, 0x3fb8aa3b, v40
	v_exp_f32_e32 v51, v40
	v_add_f32_e32 v40, v46, v87
	v_add_f32_e32 v40, v50, v40
	v_fma_f32 v36, v36, s2, -v86
	v_fma_f32 v37, v37, s2, -v86
	v_add_f32_e32 v40, v47, v40
	v_mul_f32_e32 v36, 0x3fb8aa3b, v36
	v_mul_f32_e32 v37, 0x3fb8aa3b, v37
	v_add_f32_e32 v42, v51, v40
	v_exp_f32_e32 v36, v36
	v_exp_f32_e32 v40, v37
	v_fma_f32 v37, v38, s2, -v86
	v_mul_f32_e32 v37, 0x3fb8aa3b, v37
	v_fma_f32 v38, v39, s2, -v86
	v_exp_f32_e32 v37, v37
	v_mul_f32_e32 v38, 0x3fb8aa3b, v38
	v_exp_f32_e32 v41, v38
	v_add_f32_e32 v38, v36, v42
	v_add_f32_e32 v38, v40, v38
	v_fma_f32 v32, v32, s2, -v86
	v_add_f32_e32 v38, v37, v38
	v_mul_f32_e32 v32, 0x3fb8aa3b, v32
	v_add_f32_e32 v87, v41, v38
	v_exp_f32_e32 v38, v32
	v_fma_f32 v32, v33, s2, -v86
	v_mul_f32_e32 v32, 0x3fb8aa3b, v32
	v_exp_f32_e32 v42, v32
	v_fma_f32 v32, v34, s2, -v86
	v_mul_f32_e32 v32, 0x3fb8aa3b, v32
	v_exp_f32_e32 v39, v32
	v_fma_f32 v32, v35, s2, -v86
	v_mul_f32_e32 v32, 0x3fb8aa3b, v32
	v_exp_f32_e32 v43, v32
	v_add_f32_e32 v32, v38, v87
	v_add_f32_e32 v32, v42, v32
	v_fma_f32 v28, v28, s2, -v86
	v_fma_f32 v29, v29, s2, -v86
	v_add_f32_e32 v32, v39, v32
	v_mul_f32_e32 v28, 0x3fb8aa3b, v28
	v_mul_f32_e32 v29, 0x3fb8aa3b, v29
	v_add_f32_e32 v34, v43, v32
	v_exp_f32_e32 v28, v28
	v_exp_f32_e32 v32, v29
	v_fma_f32 v29, v30, s2, -v86
	v_mul_f32_e32 v29, 0x3fb8aa3b, v29
	v_fma_f32 v30, v31, s2, -v86
	v_exp_f32_e32 v29, v29
	v_mul_f32_e32 v30, 0x3fb8aa3b, v30
	v_exp_f32_e32 v33, v30
	v_add_f32_e32 v30, v28, v34
	v_add_f32_e32 v30, v32, v30
	v_fma_f32 v24, v24, s2, -v86
	v_add_f32_e32 v30, v29, v30
	v_mul_f32_e32 v24, 0x3fb8aa3b, v24
	v_add_f32_e32 v87, v33, v30
	v_exp_f32_e32 v30, v24
	v_fma_f32 v24, v25, s2, -v86
	v_mul_f32_e32 v24, 0x3fb8aa3b, v24
	v_exp_f32_e32 v34, v24
	v_fma_f32 v24, v26, s2, -v86
	v_mul_f32_e32 v24, 0x3fb8aa3b, v24
	v_exp_f32_e32 v31, v24
	v_fma_f32 v24, v27, s2, -v86
	v_mul_f32_e32 v24, 0x3fb8aa3b, v24
	v_exp_f32_e32 v35, v24
	v_add_f32_e32 v24, v30, v87
	v_add_f32_e32 v24, v34, v24
	v_fma_f32 v20, v20, s2, -v86
	v_fma_f32 v21, v21, s2, -v86
	v_add_f32_e32 v24, v31, v24
	v_mul_f32_e32 v20, 0x3fb8aa3b, v20
	v_mul_f32_e32 v21, 0x3fb8aa3b, v21
	v_add_f32_e32 v26, v35, v24
	v_exp_f32_e32 v20, v20
	v_exp_f32_e32 v24, v21
	v_fma_f32 v21, v22, s2, -v86
	v_mul_f32_e32 v21, 0x3fb8aa3b, v21
	v_fma_f32 v22, v23, s2, -v86
	v_exp_f32_e32 v21, v21
	v_mul_f32_e32 v22, 0x3fb8aa3b, v22
	v_exp_f32_e32 v25, v22
	v_add_f32_e32 v22, v20, v26
	v_add_f32_e32 v22, v24, v22
	v_fma_f32 v16, v16, s2, -v86
	v_add_f32_e32 v22, v21, v22
	v_mul_f32_e32 v16, 0x3fb8aa3b, v16
	v_add_f32_e32 v87, v25, v22
	v_exp_f32_e32 v22, v16
	v_fma_f32 v16, v17, s2, -v86
	v_mul_f32_e32 v16, 0x3fb8aa3b, v16
	v_exp_f32_e32 v26, v16
	v_fma_f32 v16, v18, s2, -v86
	v_mul_f32_e32 v16, 0x3fb8aa3b, v16
	v_exp_f32_e32 v23, v16
	v_fma_f32 v16, v19, s2, -v86
	v_mul_f32_e32 v16, 0x3fb8aa3b, v16
	v_exp_f32_e32 v27, v16
	v_add_f32_e32 v16, v22, v87
	v_add_f32_e32 v16, v26, v16
	v_fma_f32 v12, v12, s2, -v86
	v_fma_f32 v13, v13, s2, -v86
	v_add_f32_e32 v16, v23, v16
	v_mul_f32_e32 v12, 0x3fb8aa3b, v12
	v_mul_f32_e32 v13, 0x3fb8aa3b, v13
	v_add_f32_e32 v18, v27, v16
	v_exp_f32_e32 v12, v12
	v_exp_f32_e32 v16, v13
	v_fma_f32 v13, v14, s2, -v86
	v_mul_f32_e32 v13, 0x3fb8aa3b, v13
	v_fma_f32 v14, v15, s2, -v86
	v_exp_f32_e32 v13, v13
	v_mul_f32_e32 v14, 0x3fb8aa3b, v14
	v_exp_f32_e32 v17, v14
	v_add_f32_e32 v14, v12, v18
	v_add_f32_e32 v14, v16, v14
	v_fma_f32 v8, v8, s2, -v86
	v_fma_f32 v9, v9, s2, -v86
	v_add_f32_e32 v14, v13, v14
	v_mul_f32_e32 v8, 0x3fb8aa3b, v8
	v_mul_f32_e32 v9, 0x3fb8aa3b, v9
	v_add_f32_e32 v18, v17, v14
	v_exp_f32_e32 v8, v8
	v_exp_f32_e32 v14, v9
	v_fma_f32 v9, v10, s2, -v86
	v_mul_f32_e32 v9, 0x3fb8aa3b, v9
	v_fma_f32 v10, v11, s2, -v86
	v_exp_f32_e32 v9, v9
	v_mul_f32_e32 v10, 0x3fb8aa3b, v10
	v_exp_f32_e32 v15, v10
	v_add_f32_e32 v10, v8, v18
	v_add_f32_e32 v10, v14, v10
	v_add_f32_e32 v10, v9, v10
	v_add_f32_e32 v10, v15, v10
	ds_bpermute_b32 v11, v83, v10
	s_waitcnt lgkmcnt(0)
	v_add_f32_e32 v10, v10, v11
	ds_bpermute_b32 v11, v84, v10
	s_waitcnt lgkmcnt(0)
	v_add_f32_e32 v10, v10, v11
	v_div_scale_f32 v11, s[2:3], v10, v10, 1.0
	v_rcp_f32_e32 v18, v11
	v_div_scale_f32 v19, vcc, 1.0, v10, 1.0
	v_fma_f32 v86, -v11, v18, 1.0
	v_fmac_f32_e32 v18, v86, v18
	v_mul_f32_e32 v86, v19, v18
	v_fma_f32 v87, -v11, v86, v19
	v_fmac_f32_e32 v86, v87, v18
	v_fma_f32 v11, -v11, v86, v19
	v_div_fmas_f32 v11, v11, v18, v86
	v_div_fixup_f32 v10, v11, v10, 1.0
	v_pk_mul_f32 v[18:19], v[68:69], v[10:11] op_sel_hi:[1,0]
	v_pk_mul_f32 v[68:69], v[72:73], v[10:11] op_sel_hi:[1,0]
	v_pk_mul_f32 v[72:73], v[74:75], v[10:11] op_sel_hi:[1,0]
	v_pk_mul_f32 v[70:71], v[70:71], v[10:11] op_sel_hi:[1,0]
	v_bfe_u32 v11, v73, 16, 1
	v_bfe_u32 v74, v72, 16, 1
	v_bfe_u32 v75, v69, 16, 1
	v_bfe_u32 v86, v68, 16, 1
	v_add3_u32 v73, v73, v11, s33
	v_bfe_u32 v11, v18, 16, 1
	v_add3_u32 v86, v68, v86, s33
	v_add3_u32 v87, v69, v75, s33
	v_add3_u32 v72, v72, v74, s33
	v_bfe_u32 v68, v19, 16, 1
	v_bfe_u32 v69, v70, 16, 1
	v_bfe_u32 v74, v71, 16, 1
	v_add3_u32 v18, v18, v11, s33
	v_add_u32_e32 v11, 0x9000, v85
	v_add3_u32 v74, v71, v74, s33
	v_add3_u32 v75, v70, v69, s33
	v_add3_u32 v19, v19, v68, s33
	ds_read2_b64 v[68:71], v11 offset1:4
	v_lshrrev_b32_e32 v18, 16, v18
	v_lshrrev_b32_e32 v19, 16, v19
	v_lshrrev_b32_e32 v88, 16, v75
	v_lshrrev_b32_e32 v74, 16, v74
	v_and_or_b32 v75, v73, s29, v74
	v_and_or_b32 v74, v72, s29, v88
	v_and_or_b32 v73, v87, s29, v19
	v_and_or_b32 v72, v86, s29, v18
	v_add_u32_e32 v18, 0xb000, v85
	s_waitcnt lgkmcnt(0)
	v_mfma_f32_16x16x32_bf16 v[86:89], v[68:71], v[72:75], 0
	ds_read2_b64 v[68:71], v18 offset0:32 offset1:36
	s_waitcnt lgkmcnt(0)
	v_mfma_f32_16x16x32_bf16 v[90:93], v[68:71], v[72:75], 0
	v_add_u32_e32 v68, 0xd000, v85
	v_add_u32_e32 v69, 0xf000, v85
	ds_read2_b64 v[94:97], v68 offset0:64 offset1:68
	ds_read2_b64 v[98:101], v69 offset0:96 offset1:100
	s_waitcnt lgkmcnt(1)
	v_mfma_f32_16x16x32_bf16 v[94:97], v[94:97], v[72:75], 0
	s_waitcnt lgkmcnt(0)
	v_mfma_f32_16x16x32_bf16 v[70:73], v[98:101], v[72:75], 0
	ds_read2_b64 v[132:135], v11 offset0:8 offset1:12
	ds_read2_b64 v[136:139], v18 offset0:40 offset1:44
	ds_read2_b64 v[140:143], v68 offset0:72 offset1:76
	ds_read2_b64 v[144:147], v69 offset0:104 offset1:108
	v_mul_f32_e64 v64, v64, v10
	v_mul_f32_e64 v65, v65, v10
	v_pk_mul_f32 v[66:67], v[66:67], v[10:11] op_sel_hi:[1,0]
	v_pk_mul_f32 v[60:61], v[60:61], v[10:11] op_sel_hi:[1,0]
	v_pk_mul_f32 v[62:63], v[62:63], v[10:11] op_sel_hi:[1,0]
	v_bfe_u32 v19, v67, 16, 1
	v_bfe_u32 v74, v66, 16, 1
	v_bfe_u32 v75, v65, 16, 1
	v_bfe_u32 v98, v64, 16, 1
	v_add3_u32 v64, v64, v98, s33
	v_add3_u32 v65, v65, v75, s33
	v_add3_u32 v66, v66, v74, s33
	v_add3_u32 v19, v67, v19, s33
	v_bfe_u32 v67, v60, 16, 1
	v_bfe_u32 v74, v61, 16, 1
	v_bfe_u32 v75, v62, 16, 1
	v_bfe_u32 v98, v63, 16, 1
	v_add3_u32 v98, v63, v98, s33
	v_add3_u32 v75, v62, v75, s33
	v_add3_u32 v74, v61, v74, s33
	v_add3_u32 v67, v60, v67, s33
	v_lshrrev_b32_e32 v99, 16, v67
	v_lshrrev_b32_e32 v74, 16, v74
	v_lshrrev_b32_e32 v75, 16, v75
	v_lshrrev_b32_e32 v67, 16, v98
	v_and_or_b32 v67, v19, s29, v67
	v_and_or_b32 v66, v66, s29, v75
	v_and_or_b32 v65, v65, s29, v74
	v_and_or_b32 v64, v64, s29, v99
	s_waitcnt lgkmcnt(3)
	s_nop 1
	v_mfma_f32_16x16x32_bf16 v[60:63], v[132:135], v[64:67], v[86:89]
	s_waitcnt lgkmcnt(2)
	v_mfma_f32_16x16x32_bf16 v[86:89], v[136:139], v[64:67], v[90:93]
	s_waitcnt lgkmcnt(1)
	v_mfma_f32_16x16x32_bf16 v[90:93], v[140:143], v[64:67], v[94:97]
	s_waitcnt lgkmcnt(0)
	v_mfma_f32_16x16x32_bf16 v[64:67], v[144:147], v[64:67], v[70:73]
	ds_read2_b64 v[116:119], v11 offset0:16 offset1:20
	ds_read2_b64 v[120:123], v18 offset0:48 offset1:52
	ds_read2_b64 v[124:127], v68 offset0:80 offset1:84
	ds_read2_b64 v[128:131], v69 offset0:112 offset1:116
	v_mul_f32_e64 v56, v56, v10
	v_mul_f32_e64 v57, v57, v10
	v_pk_mul_f32 v[58:59], v[58:59], v[10:11] op_sel_hi:[1,0]
	v_pk_mul_f32 v[52:53], v[52:53], v[10:11] op_sel_hi:[1,0]
	v_pk_mul_f32 v[54:55], v[54:55], v[10:11] op_sel_hi:[1,0]
	v_bfe_u32 v19, v59, 16, 1
	v_bfe_u32 v70, v58, 16, 1
	v_bfe_u32 v71, v57, 16, 1
	v_bfe_u32 v72, v56, 16, 1
	v_add3_u32 v56, v56, v72, s33
	v_add3_u32 v57, v57, v71, s33
	v_add3_u32 v58, v58, v70, s33
	v_add3_u32 v19, v59, v19, s33
	v_bfe_u32 v59, v52, 16, 1
	v_bfe_u32 v70, v53, 16, 1
	v_bfe_u32 v71, v54, 16, 1
	v_bfe_u32 v72, v55, 16, 1
	v_add3_u32 v72, v55, v72, s33
	v_add3_u32 v71, v54, v71, s33
	v_add3_u32 v70, v53, v70, s33
	v_add3_u32 v59, v52, v59, s33
	v_lshrrev_b32_e32 v73, 16, v59
	v_lshrrev_b32_e32 v70, 16, v70
	v_lshrrev_b32_e32 v71, 16, v71
	v_lshrrev_b32_e32 v59, 16, v72
	v_and_or_b32 v59, v19, s29, v59
	v_and_or_b32 v58, v58, s29, v71
	v_and_or_b32 v57, v57, s29, v70
	v_and_or_b32 v56, v56, s29, v73
	s_waitcnt lgkmcnt(3)
	s_nop 1
	v_mfma_f32_16x16x32_bf16 v[52:55], v[116:119], v[56:59], v[60:63]
	s_waitcnt lgkmcnt(2)
	v_mfma_f32_16x16x32_bf16 v[60:63], v[120:123], v[56:59], v[86:89]
	s_waitcnt lgkmcnt(1)
	v_mfma_f32_16x16x32_bf16 v[70:73], v[124:127], v[56:59], v[90:93]
	s_waitcnt lgkmcnt(0)
	v_mfma_f32_16x16x32_bf16 v[56:59], v[128:131], v[56:59], v[64:67]
	ds_read2_b64 v[132:135], v11 offset0:24 offset1:28
	ds_read2_b64 v[136:139], v18 offset0:56 offset1:60
	ds_read2_b64 v[140:143], v68 offset0:88 offset1:92
	ds_read2_b64 v[144:147], v69 offset0:120 offset1:124
	v_mul_f32_e64 v48, v48, v10
	v_mul_f32_e64 v49, v49, v10
	v_pk_mul_f32 v[50:51], v[50:51], v[10:11] op_sel_hi:[1,0]
	v_pk_mul_f32 v[44:45], v[44:45], v[10:11] op_sel_hi:[1,0]
	v_pk_mul_f32 v[46:47], v[46:47], v[10:11] op_sel_hi:[1,0]
	v_bfe_u32 v19, v51, 16, 1
	v_bfe_u32 v64, v50, 16, 1
	v_bfe_u32 v65, v49, 16, 1
	v_bfe_u32 v66, v48, 16, 1
	v_add3_u32 v48, v48, v66, s33
	v_add3_u32 v49, v49, v65, s33
	v_add3_u32 v50, v50, v64, s33
	v_add3_u32 v19, v51, v19, s33
	v_bfe_u32 v51, v44, 16, 1
	v_bfe_u32 v64, v45, 16, 1
	v_bfe_u32 v65, v46, 16, 1
	v_bfe_u32 v66, v47, 16, 1
	v_add3_u32 v66, v47, v66, s33
	v_add3_u32 v65, v46, v65, s33
	v_add3_u32 v64, v45, v64, s33
	v_add3_u32 v51, v44, v51, s33
	v_lshrrev_b32_e32 v67, 16, v51
	v_lshrrev_b32_e32 v64, 16, v64
	v_lshrrev_b32_e32 v65, 16, v65
	v_lshrrev_b32_e32 v51, 16, v66
	v_and_or_b32 v51, v19, s29, v51
	v_and_or_b32 v50, v50, s29, v65
	v_and_or_b32 v49, v49, s29, v64
	v_and_or_b32 v48, v48, s29, v67
	s_waitcnt lgkmcnt(3)
	s_nop 1
	v_mfma_f32_16x16x32_bf16 v[44:47], v[132:135], v[48:51], v[52:55]
	s_waitcnt lgkmcnt(2)
	v_mfma_f32_16x16x32_bf16 v[52:55], v[136:139], v[48:51], v[60:63]
	s_waitcnt lgkmcnt(1)
	v_mfma_f32_16x16x32_bf16 v[60:63], v[140:143], v[48:51], v[70:73]
	s_waitcnt lgkmcnt(0)
	v_mfma_f32_16x16x32_bf16 v[48:51], v[144:147], v[48:51], v[56:59]
	ds_read2_b64 v[116:119], v11 offset0:32 offset1:36
	ds_read2_b64 v[120:123], v18 offset0:64 offset1:68
	ds_read2_b64 v[124:127], v68 offset0:96 offset1:100
	ds_read2_b64 v[128:131], v69 offset0:128 offset1:132
	v_mul_f32_e64 v40, v40, v10
	v_mul_f32_e64 v41, v41, v10
	v_pk_mul_f32 v[42:43], v[42:43], v[10:11] op_sel_hi:[1,0]
	v_pk_mul_f32 v[36:37], v[36:37], v[10:11] op_sel_hi:[1,0]
	v_pk_mul_f32 v[38:39], v[38:39], v[10:11] op_sel_hi:[1,0]
	v_bfe_u32 v19, v43, 16, 1
	v_bfe_u32 v56, v42, 16, 1
	v_bfe_u32 v57, v41, 16, 1
	v_bfe_u32 v58, v40, 16, 1
	v_add3_u32 v40, v40, v58, s33
	v_add3_u32 v41, v41, v57, s33
	v_add3_u32 v42, v42, v56, s33
	v_add3_u32 v19, v43, v19, s33
	v_bfe_u32 v43, v36, 16, 1
	v_bfe_u32 v56, v37, 16, 1
	v_bfe_u32 v57, v38, 16, 1
	v_bfe_u32 v58, v39, 16, 1
	v_add3_u32 v58, v39, v58, s33
	v_add3_u32 v57, v38, v57, s33
	v_add3_u32 v56, v37, v56, s33
	v_add3_u32 v43, v36, v43, s33
	v_lshrrev_b32_e32 v59, 16, v43
	v_lshrrev_b32_e32 v56, 16, v56
	v_lshrrev_b32_e32 v57, 16, v57
	v_lshrrev_b32_e32 v43, 16, v58
	v_and_or_b32 v43, v19, s29, v43
	v_and_or_b32 v42, v42, s29, v57
	v_and_or_b32 v41, v41, s29, v56
	v_and_or_b32 v40, v40, s29, v59
	s_waitcnt lgkmcnt(3)
	s_nop 1
	v_mfma_f32_16x16x32_bf16 v[36:39], v[116:119], v[40:43], v[44:47]
	s_waitcnt lgkmcnt(2)
	v_mfma_f32_16x16x32_bf16 v[44:47], v[120:123], v[40:43], v[52:55]
	s_waitcnt lgkmcnt(1)
	v_mfma_f32_16x16x32_bf16 v[52:55], v[124:127], v[40:43], v[60:63]
	s_waitcnt lgkmcnt(0)
	v_mfma_f32_16x16x32_bf16 v[40:43], v[128:131], v[40:43], v[48:51]
	ds_read2_b64 v[132:135], v11 offset0:40 offset1:44
	ds_read2_b64 v[136:139], v18 offset0:72 offset1:76
	ds_read2_b64 v[140:143], v68 offset0:104 offset1:108
	ds_read2_b64 v[144:147], v69 offset0:136 offset1:140
	v_mul_f32_e64 v32, v32, v10
	v_mul_f32_e64 v33, v33, v10
	v_pk_mul_f32 v[34:35], v[34:35], v[10:11] op_sel_hi:[1,0]
	v_pk_mul_f32 v[28:29], v[28:29], v[10:11] op_sel_hi:[1,0]
	v_pk_mul_f32 v[30:31], v[30:31], v[10:11] op_sel_hi:[1,0]
	v_bfe_u32 v19, v35, 16, 1
	v_bfe_u32 v48, v34, 16, 1
	v_bfe_u32 v49, v33, 16, 1
	v_bfe_u32 v50, v32, 16, 1
	v_add3_u32 v32, v32, v50, s33
	v_add3_u32 v33, v33, v49, s33
	v_add3_u32 v34, v34, v48, s33
	v_add3_u32 v19, v35, v19, s33
	v_bfe_u32 v35, v28, 16, 1
	v_bfe_u32 v48, v29, 16, 1
	v_bfe_u32 v49, v30, 16, 1
	v_bfe_u32 v50, v31, 16, 1
	v_add3_u32 v50, v31, v50, s33
	v_add3_u32 v49, v30, v49, s33
	v_add3_u32 v48, v29, v48, s33
	v_add3_u32 v35, v28, v35, s33
	v_lshrrev_b32_e32 v51, 16, v35
	v_lshrrev_b32_e32 v48, 16, v48
	v_lshrrev_b32_e32 v49, 16, v49
	v_lshrrev_b32_e32 v35, 16, v50
	v_and_or_b32 v35, v19, s29, v35
	v_and_or_b32 v34, v34, s29, v49
	v_and_or_b32 v33, v33, s29, v48
	v_and_or_b32 v32, v32, s29, v51
	s_waitcnt lgkmcnt(3)
	s_nop 1
	v_mfma_f32_16x16x32_bf16 v[28:31], v[132:135], v[32:35], v[36:39]
	s_waitcnt lgkmcnt(2)
	v_mfma_f32_16x16x32_bf16 v[36:39], v[136:139], v[32:35], v[44:47]
	s_waitcnt lgkmcnt(1)
	v_mfma_f32_16x16x32_bf16 v[44:47], v[140:143], v[32:35], v[52:55]
	s_waitcnt lgkmcnt(0)
	v_mfma_f32_16x16x32_bf16 v[32:35], v[144:147], v[32:35], v[40:43]
	ds_read2_b64 v[116:119], v11 offset0:48 offset1:52
	ds_read2_b64 v[120:123], v18 offset0:80 offset1:84
	ds_read2_b64 v[124:127], v68 offset0:112 offset1:116
	ds_read2_b64 v[128:131], v69 offset0:144 offset1:148
	v_mul_f32_e64 v24, v24, v10
	v_mul_f32_e64 v25, v25, v10
	v_pk_mul_f32 v[26:27], v[26:27], v[10:11] op_sel_hi:[1,0]
	v_pk_mul_f32 v[20:21], v[20:21], v[10:11] op_sel_hi:[1,0]
	v_pk_mul_f32 v[22:23], v[22:23], v[10:11] op_sel_hi:[1,0]
	v_bfe_u32 v19, v27, 16, 1
	v_bfe_u32 v40, v26, 16, 1
	v_bfe_u32 v41, v25, 16, 1
	v_bfe_u32 v42, v24, 16, 1
	v_add3_u32 v24, v24, v42, s33
	v_add3_u32 v25, v25, v41, s33
	v_add3_u32 v26, v26, v40, s33
	v_add3_u32 v19, v27, v19, s33
	v_bfe_u32 v27, v20, 16, 1
	v_bfe_u32 v40, v21, 16, 1
	v_bfe_u32 v41, v22, 16, 1
	v_bfe_u32 v42, v23, 16, 1
	v_add3_u32 v42, v23, v42, s33
	v_add3_u32 v41, v22, v41, s33
	v_add3_u32 v40, v21, v40, s33
	v_add3_u32 v27, v20, v27, s33
	v_lshrrev_b32_e32 v43, 16, v27
	v_lshrrev_b32_e32 v40, 16, v40
	v_lshrrev_b32_e32 v41, 16, v41
	v_lshrrev_b32_e32 v27, 16, v42
	v_and_or_b32 v27, v19, s29, v27
	v_and_or_b32 v26, v26, s29, v41
	v_and_or_b32 v25, v25, s29, v40
	v_and_or_b32 v24, v24, s29, v43
	s_waitcnt lgkmcnt(3)
	s_nop 1
	v_mfma_f32_16x16x32_bf16 v[20:23], v[116:119], v[24:27], v[28:31]
	s_waitcnt lgkmcnt(2)
	v_mfma_f32_16x16x32_bf16 v[28:31], v[120:123], v[24:27], v[36:39]
	s_waitcnt lgkmcnt(1)
	v_mfma_f32_16x16x32_bf16 v[36:39], v[124:127], v[24:27], v[44:47]
	s_waitcnt lgkmcnt(0)
	v_mfma_f32_16x16x32_bf16 v[24:27], v[128:131], v[24:27], v[32:35]
	ds_read2_b64 v[132:135], v11 offset0:56 offset1:60
	ds_read2_b64 v[136:139], v18 offset0:88 offset1:92
	ds_read2_b64 v[140:143], v68 offset0:120 offset1:124
	ds_read2_b64 v[144:147], v69 offset0:152 offset1:156
	v_mul_f32_e64 v16, v16, v10
	v_mul_f32_e64 v17, v17, v10
	v_pk_mul_f32 v[14:15], v[14:15], v[10:11] op_sel_hi:[1,0]
	v_pk_mul_f32 v[12:13], v[12:13], v[10:11] op_sel_hi:[1,0]
	v_pk_mul_f32 v[8:9], v[8:9], v[10:11] op_sel_hi:[1,0]
	v_bfe_u32 v10, v15, 16, 1
	v_bfe_u32 v32, v17, 16, 1
	v_bfe_u32 v33, v16, 16, 1
	v_add3_u32 v16, v16, v33, s33
	v_add3_u32 v17, v17, v32, s33
	v_add3_u32 v15, v15, v10, s33
	v_bfe_u32 v10, v12, 16, 1
	v_bfe_u32 v32, v8, 16, 1
	v_bfe_u32 v33, v9, 16, 1
	v_add3_u32 v33, v9, v33, s33
	v_add3_u32 v32, v8, v32, s33
	v_add3_u32 v12, v12, v10, s33
	v_bfe_u32 v19, v14, 16, 1
	v_add3_u32 v14, v14, v19, s33
	v_bfe_u32 v19, v13, 16, 1
	v_add3_u32 v13, v13, v19, s33
	v_lshrrev_b32_e32 v12, 16, v12
	v_lshrrev_b32_e32 v13, 16, v13
	v_lshrrev_b32_e32 v19, 16, v32
	v_lshrrev_b32_e32 v32, 16, v33
	v_and_or_b32 v35, v15, s29, v32
	v_and_or_b32 v34, v14, s29, v19
	v_and_or_b32 v33, v17, s29, v13
	v_and_or_b32 v32, v16, s29, v12
	s_waitcnt lgkmcnt(3)
	s_nop 1
	v_mfma_f32_16x16x32_bf16 v[20:23], v[132:135], v[32:35], v[20:23]
	s_waitcnt lgkmcnt(2)
	v_mfma_f32_16x16x32_bf16 v[16:19], v[136:139], v[32:35], v[28:31]
	s_waitcnt lgkmcnt(1)
	v_mfma_f32_16x16x32_bf16 v[12:15], v[140:143], v[32:35], v[36:39]
	s_waitcnt lgkmcnt(0)
	v_mfma_f32_16x16x32_bf16 v[8:11], v[144:147], v[32:35], v[24:27]
	s_and_saveexec_b64 s[2:3], s[0:1]
	s_cbranch_execz .LBB0_253
	s_nop 0
	v_bfe_u32 v26, v20, 16, 1
	v_add3_u32 v20, v20, v26, s33
	v_bfe_u32 v26, v21, 16, 1
	v_add3_u32 v21, v21, v26, s33
	v_lshrrev_b32_e32 v20, 16, v20
	v_add_u32_e32 v24, s6, v81
	v_and_or_b32 v20, v21, s29, v20
	v_bfe_u32 v21, v22, 16, 1
	v_ashrrev_i32_e32 v25, 31, v24
	v_add3_u32 v21, v22, v21, s33
	v_bfe_u32 v22, v23, 16, 1
	v_lshlrev_b64 v[24:25], 11, v[24:25]
	v_add3_u32 v22, v23, v22, s33
	v_lshrrev_b32_e32 v21, 16, v21
	v_lshl_add_u64 v[24:25], v[76:77], 0, v[24:25]
	v_and_or_b32 v21, v22, s29, v21
	global_store_dwordx2 v[24:25], v[20:21], off offset:1536
	v_bfe_u32 v20, v16, 16, 1
	v_add3_u32 v16, v16, v20, s33
	v_bfe_u32 v20, v17, 16, 1
	v_add3_u32 v17, v17, v20, s33
	v_lshrrev_b32_e32 v16, 16, v16
	v_and_or_b32 v16, v17, s29, v16
	v_bfe_u32 v17, v18, 16, 1
	v_add3_u32 v17, v18, v17, s33
	v_bfe_u32 v18, v19, 16, 1
	v_add3_u32 v18, v19, v18, s33
	v_lshrrev_b32_e32 v17, 16, v17
	v_and_or_b32 v17, v18, s29, v17
	global_store_dwordx2 v[24:25], v[16:17], off offset:1568
	v_bfe_u32 v16, v12, 16, 1
	v_add3_u32 v12, v12, v16, s33
	v_bfe_u32 v16, v13, 16, 1
	v_add3_u32 v13, v13, v16, s33
	v_lshrrev_b32_e32 v12, 16, v12
	v_and_or_b32 v12, v13, s29, v12
	v_bfe_u32 v13, v14, 16, 1
	v_add3_u32 v13, v14, v13, s33
	v_bfe_u32 v14, v15, 16, 1
	v_add3_u32 v14, v15, v14, s33
	v_lshrrev_b32_e32 v13, 16, v13
	v_and_or_b32 v13, v14, s29, v13
	global_store_dwordx2 v[24:25], v[12:13], off offset:1600
	v_bfe_u32 v12, v8, 16, 1
	v_add3_u32 v8, v8, v12, s33
	v_bfe_u32 v12, v9, 16, 1
	v_add3_u32 v9, v9, v12, s33
	v_lshrrev_b32_e32 v8, 16, v8
	v_and_or_b32 v8, v9, s29, v8
	v_bfe_u32 v9, v10, 16, 1
	v_add3_u32 v9, v10, v9, s33
	v_bfe_u32 v10, v11, 16, 1
	v_add3_u32 v10, v11, v10, s33
	v_lshrrev_b32_e32 v9, 16, v9
	v_and_or_b32 v9, v10, s29, v9
	global_store_dwordx2 v[24:25], v[8:9], off offset:1632
	s_branch .LBB0_253

.LBB0_319:
	v_readlane_b32 s8, v249, 63
	v_mul_f32_e32 v8, 0x3e000000, v8
	v_readlane_b32 s9, v248, 0
	v_mul_f32_e32 v9, 0x3e000000, v9
	v_mul_f32_e32 v10, 0x3e000000, v10
	v_cndmask_b32_e64 v8, v230, v8, s[8:9]
	v_readlane_b32 s8, v248, 1
	v_readlane_b32 s9, v248, 2
	v_mul_f32_e32 v34, 0x3e000000, v37
	v_mul_f32_e32 v11, 0x3e000000, v11
	v_cndmask_b32_e64 v9, v230, v9, s[8:9]
	v_readlane_b32 s8, v248, 3
	v_readlane_b32 s9, v248, 4
	v_cndmask_b32_e64 v69, v230, v34, s[44:45]
	v_mul_f32_e32 v34, 0x3e000000, v38
	v_cndmask_b32_e64 v10, v230, v10, s[8:9]
	v_readlane_b32 s8, v248, 5
	v_readlane_b32 s9, v248, 6
	v_cndmask_b32_e64 v70, v230, v34, s[46:47]
	v_mul_f32_e32 v34, 0x3e000000, v39
	v_cndmask_b32_e64 v11, v230, v11, s[8:9]
	v_readlane_b32 s8, v248, 7
	v_max3_f32 v32, v68, v8, v9
	v_mul_f32_e32 v12, 0x3e000000, v12
	v_readlane_b32 s9, v248, 8
	v_mul_f32_e32 v13, 0x3e000000, v13
	v_cndmask_b32_e64 v71, v230, v34, s[48:49]
	v_mul_f32_e32 v34, 0x3e000000, v40
	v_max3_f32 v32, v32, v10, v11
	v_cndmask_b32_e64 v12, v230, v12, s[8:9]
	v_cndmask_b32_e64 v13, v230, v13, s[10:11]
	v_mul_f32_e32 v14, 0x3e000000, v14
	v_mul_f32_e32 v15, 0x3e000000, v15
	v_cndmask_b32_e64 v75, v230, v34, s[50:51]
	v_mul_f32_e32 v34, 0x3e000000, v41
	v_max3_f32 v32, v32, v12, v13
	v_cndmask_b32_e64 v14, v230, v14, s[12:13]
	v_cndmask_b32_e64 v15, v230, v15, s[14:15]
	v_mul_f32_e32 v20, 0x3e000000, v20
	v_mul_f32_e32 v21, 0x3e000000, v21
	v_cndmask_b32_e64 v76, v230, v34, s[52:53]
	v_mul_f32_e32 v34, 0x3e000000, v42
	v_max3_f32 v32, v32, v14, v15
	v_cndmask_b32_e64 v20, v230, v20, s[16:17]
	v_cndmask_b32_e64 v21, v230, v21, s[18:19]
	v_mul_f32_e32 v22, 0x3e000000, v22
	v_mul_f32_e32 v23, 0x3e000000, v23
	v_cndmask_b32_e64 v77, v230, v34, s[54:55]
	v_mul_f32_e32 v34, 0x3e000000, v43
	v_max3_f32 v32, v32, v20, v21
	v_cndmask_b32_e64 v22, v230, v22, s[20:21]
	v_cndmask_b32_e64 v23, v230, v23, s[22:23]
	v_mul_f32_e32 v24, 0x3e000000, v24
	v_mul_f32_e32 v25, 0x3e000000, v25
	v_cndmask_b32_e64 v78, v230, v34, s[56:57]
	v_mul_f32_e32 v34, 0x3e000000, v44
	v_max3_f32 v32, v32, v22, v23
	v_cndmask_b32_e64 v24, v230, v24, s[24:25]
	v_cndmask_b32_e64 v25, v230, v25, s[26:27]
	v_mul_f32_e32 v26, 0x3e000000, v26
	v_mul_f32_e32 v27, 0x3e000000, v27
	v_cndmask_b32_e64 v79, v230, v34, s[58:59]
	v_mul_f32_e32 v34, 0x3e000000, v45
	v_max3_f32 v32, v32, v24, v25
	v_cndmask_b32_e64 v26, v230, v26, s[4:5]
	v_cndmask_b32_e64 v27, v230, v27, s[30:31]
	v_mul_f32_e32 v28, 0x3e000000, v28
	v_mul_f32_e32 v29, 0x3e000000, v29
	v_cndmask_b32_e64 v81, v230, v34, s[60:61]
	v_mul_f32_e32 v34, 0x3e000000, v46
	v_max3_f32 v32, v32, v26, v27
	v_cndmask_b32_e64 v28, v230, v28, s[34:35]
	v_cndmask_b32_e64 v29, v230, v29, s[36:37]
	v_mul_f32_e32 v30, 0x3e000000, v30
	v_mul_f32_e32 v31, 0x3e000000, v31
	v_cndmask_b32_e64 v82, v230, v34, s[62:63]
	v_mul_f32_e32 v34, 0x3e000000, v47
	v_max3_f32 v32, v32, v28, v29
	v_cndmask_b32_e64 v30, v230, v30, s[38:39]
	v_cndmask_b32_e64 v31, v230, v31, s[40:41]
	v_mul_f32_e32 v33, 0x3e000000, v36
	v_cndmask_b32_e64 v83, v230, v34, s[64:65]
	v_mul_f32_e32 v34, 0x3e000000, v48
	v_max3_f32 v32, v32, v30, v31
	v_cndmask_b32_e64 v33, v230, v33, s[42:43]
	v_cndmask_b32_e64 v84, v230, v34, s[66:67]
	v_mul_f32_e32 v34, 0x3e000000, v49
	v_max3_f32 v32, v32, v33, v69
	v_cndmask_b32_e64 v85, v230, v34, s[68:69]
	v_mul_f32_e32 v34, 0x3e000000, v50
	v_max3_f32 v32, v32, v70, v71
	v_cndmask_b32_e64 v86, v230, v34, s[70:71]
	v_mul_f32_e32 v34, 0x3e000000, v51
	v_max3_f32 v32, v32, v75, v76
	v_cndmask_b32_e64 v87, v230, v34, s[72:73]
	v_mul_f32_e32 v34, 0x3e000000, v52
	v_max3_f32 v32, v32, v77, v78
	v_cndmask_b32_e64 v88, v230, v34, s[74:75]
	v_mul_f32_e32 v34, 0x3e000000, v53
	v_max3_f32 v32, v32, v79, v81
	v_cndmask_b32_e64 v89, v230, v34, s[76:77]
	v_mul_f32_e32 v34, 0x3e000000, v54
	v_max3_f32 v32, v32, v82, v83
	v_cndmask_b32_e64 v90, v230, v34, s[78:79]
	v_mul_f32_e32 v34, 0x3e000000, v55
	v_max3_f32 v32, v32, v84, v85
	v_cndmask_b32_e64 v91, v230, v34, s[80:81]
	v_mul_f32_e32 v34, 0x3e000000, v56
	v_max3_f32 v32, v32, v86, v87
	v_cndmask_b32_e64 v92, v230, v34, s[82:83]
	v_mul_f32_e32 v34, 0x3e000000, v57
	v_max3_f32 v32, v32, v88, v89
	v_cndmask_b32_e64 v93, v230, v34, s[84:85]
	v_mul_f32_e32 v34, 0x3e000000, v58
	v_max3_f32 v32, v32, v90, v91
	v_cndmask_b32_e64 v58, v230, v34, s[86:87]
	v_mul_f32_e32 v34, 0x3e000000, v59
	v_mul_f32_e32 v16, 0x3e000000, v16
	v_max3_f32 v32, v32, v92, v93
	v_cndmask_b32_e64 v59, v230, v34, s[88:89]
	v_cndmask_b32_e64 v94, v230, v16, s[90:91]
	v_mul_f32_e32 v16, 0x3e000000, v17
	v_mul_f32_e32 v17, 0x3e000000, v18
	v_max3_f32 v32, v32, v58, v59
	v_cndmask_b32_e64 v95, v230, v16, s[92:93]
	v_cndmask_b32_e64 v96, v230, v17, s[94:95]
	v_mul_f32_e32 v17, 0x3e000000, v19
	v_max3_f32 v16, v32, v94, v95
	v_cndmask_b32_e64 v97, v230, v17, s[96:97]
	v_max3_f32 v16, v16, v96, v97
	ds_bpermute_b32 v17, v64, v16
	s_waitcnt lgkmcnt(0)
	v_max_f32_e32 v17, v17, v17
	v_max_f32_e32 v16, v16, v17
	ds_bpermute_b32 v17, v65, v16
	s_waitcnt lgkmcnt(0)
	v_max_f32_e32 v17, v17, v17
	v_max_f32_e32 v98, v16, v17
	v_sub_f32_e32 v8, v8, v98
	v_mul_f32_e32 v8, 0x3fb8aa3b, v8
	v_exp_f32_e32 v50, v8
	v_sub_f32_e32 v8, v9, v98
	v_sub_f32_e32 v9, v12, v98
	v_mul_f32_e32 v9, 0x3fb8aa3b, v9
	v_exp_f32_e32 v54, v9
	v_sub_f32_e32 v9, v13, v98
	v_mul_f32_e32 v9, 0x3fb8aa3b, v9
	v_exp_f32_e32 v56, v9
	v_sub_f32_e32 v9, v14, v98
	v_mul_f32_e32 v9, 0x3fb8aa3b, v9
	v_exp_f32_e32 v55, v9
	v_sub_f32_e32 v9, v15, v98
	v_mul_f32_e32 v9, 0x3fb8aa3b, v9
	v_exp_f32_e32 v57, v9
	v_sub_f32_e32 v9, v20, v98
	v_mul_f32_e32 v9, 0x3fb8aa3b, v9
	v_exp_f32_e32 v42, v9
	v_sub_f32_e32 v9, v21, v98
	v_mul_f32_e32 v9, 0x3fb8aa3b, v9
	v_exp_f32_e32 v44, v9
	v_sub_f32_e32 v9, v22, v98
	v_mul_f32_e32 v9, 0x3fb8aa3b, v9
	v_exp_f32_e32 v43, v9
	v_sub_f32_e32 v9, v23, v98
	v_mul_f32_e32 v9, 0x3fb8aa3b, v9
	v_exp_f32_e32 v45, v9
	v_sub_f32_e32 v9, v24, v98
	v_mul_f32_e32 v9, 0x3fb8aa3b, v9
	v_exp_f32_e32 v46, v9
	v_sub_f32_e32 v9, v25, v98
	v_mul_f32_e32 v9, 0x3fb8aa3b, v9
	v_exp_f32_e32 v48, v9
	v_sub_f32_e32 v9, v26, v98
	v_mul_f32_e32 v9, 0x3fb8aa3b, v9
	v_exp_f32_e32 v47, v9
	v_sub_f32_e32 v9, v27, v98
	v_mul_f32_e32 v9, 0x3fb8aa3b, v9
	v_exp_f32_e32 v49, v9
	v_sub_f32_e32 v9, v28, v98
	v_mul_f32_e32 v9, 0x3fb8aa3b, v9
	v_exp_f32_e32 v34, v9
	v_sub_f32_e32 v9, v29, v98
	v_mul_f32_e32 v9, 0x3fb8aa3b, v9
	v_exp_f32_e32 v36, v9
	v_sub_f32_e32 v9, v30, v98
	v_mul_f32_e32 v9, 0x3fb8aa3b, v9
	v_exp_f32_e32 v35, v9
	v_sub_f32_e32 v9, v31, v98
	v_mul_f32_e32 v8, 0x3fb8aa3b, v8
	v_mul_f32_e32 v9, 0x3fb8aa3b, v9
	v_exp_f32_e32 v52, v8
	v_sub_f32_e32 v8, v10, v98
	v_exp_f32_e32 v37, v9
	v_sub_f32_e32 v9, v33, v98
	v_mul_f32_e32 v8, 0x3fb8aa3b, v8
	v_mul_f32_e32 v9, 0x3fb8aa3b, v9
	v_exp_f32_e32 v51, v8
	v_sub_f32_e32 v8, v11, v98
	v_exp_f32_e32 v38, v9
	v_sub_f32_e32 v9, v69, v98
	v_mul_f32_e32 v8, 0x3fb8aa3b, v8
	v_mul_f32_e32 v9, 0x3fb8aa3b, v9
	v_exp_f32_e32 v53, v8
	v_exp_f32_e32 v40, v9
	v_sub_f32_e32 v9, v70, v98
	v_add_f32_e32 v8, 0, v50
	v_mul_f32_e32 v9, 0x3fb8aa3b, v9
	v_add_f32_e32 v8, v52, v8
	v_exp_f32_e32 v39, v9
	v_sub_f32_e32 v9, v71, v98
	v_add_f32_e32 v8, v51, v8
	v_mul_f32_e32 v9, 0x3fb8aa3b, v9
	v_add_f32_e32 v8, v53, v8
	v_exp_f32_e32 v41, v9
	v_sub_f32_e32 v9, v75, v98
	v_add_f32_e32 v8, v54, v8
	v_mul_f32_e32 v9, 0x3fb8aa3b, v9
	v_add_f32_e32 v8, v56, v8
	v_exp_f32_e32 v26, v9
	v_sub_f32_e32 v9, v76, v98
	v_add_f32_e32 v8, v55, v8
	v_mul_f32_e32 v9, 0x3fb8aa3b, v9
	v_add_f32_e32 v8, v57, v8
	v_exp_f32_e32 v28, v9
	v_sub_f32_e32 v9, v77, v98
	v_add_f32_e32 v8, v42, v8
	v_mul_f32_e32 v9, 0x3fb8aa3b, v9
	v_add_f32_e32 v8, v44, v8
	v_exp_f32_e32 v27, v9
	v_sub_f32_e32 v9, v78, v98
	v_add_f32_e32 v8, v43, v8
	v_mul_f32_e32 v9, 0x3fb8aa3b, v9
	v_add_f32_e32 v8, v45, v8
	v_exp_f32_e32 v29, v9
	v_sub_f32_e32 v9, v79, v98
	v_add_f32_e32 v8, v46, v8
	v_mul_f32_e32 v9, 0x3fb8aa3b, v9
	v_add_f32_e32 v8, v48, v8
	v_exp_f32_e32 v30, v9
	v_sub_f32_e32 v9, v81, v98
	v_add_f32_e32 v8, v47, v8
	v_mul_f32_e32 v9, 0x3fb8aa3b, v9
	v_add_f32_e32 v8, v49, v8
	v_exp_f32_e32 v32, v9
	v_sub_f32_e32 v9, v82, v98
	v_add_f32_e32 v8, v34, v8
	v_mul_f32_e32 v9, 0x3fb8aa3b, v9
	v_add_f32_e32 v8, v36, v8
	v_exp_f32_e32 v31, v9
	v_sub_f32_e32 v9, v83, v98
	v_add_f32_e32 v8, v35, v8
	v_mul_f32_e32 v9, 0x3fb8aa3b, v9
	v_add_f32_e32 v8, v37, v8
	v_exp_f32_e32 v33, v9
	v_sub_f32_e32 v9, v84, v98
	v_add_f32_e32 v8, v38, v8
	v_mul_f32_e32 v9, 0x3fb8aa3b, v9
	v_add_f32_e32 v8, v40, v8
	v_exp_f32_e32 v16, v9
	v_sub_f32_e32 v9, v85, v98
	v_add_f32_e32 v8, v39, v8
	v_mul_f32_e32 v9, 0x3fb8aa3b, v9
	v_add_f32_e32 v8, v41, v8
	v_exp_f32_e32 v18, v9
	v_sub_f32_e32 v9, v86, v98
	v_add_f32_e32 v8, v26, v8
	v_mul_f32_e32 v9, 0x3fb8aa3b, v9
	v_add_f32_e32 v8, v28, v8
	v_exp_f32_e32 v17, v9
	v_sub_f32_e32 v9, v87, v98
	v_add_f32_e32 v8, v27, v8
	v_mul_f32_e32 v9, 0x3fb8aa3b, v9
	v_add_f32_e32 v8, v29, v8
	v_exp_f32_e32 v19, v9
	v_sub_f32_e32 v9, v88, v98
	v_add_f32_e32 v8, v30, v8
	v_mul_f32_e32 v9, 0x3fb8aa3b, v9
	v_add_f32_e32 v8, v32, v8
	v_exp_f32_e32 v22, v9
	v_sub_f32_e32 v9, v89, v98
	v_add_f32_e32 v8, v31, v8
	v_mul_f32_e32 v9, 0x3fb8aa3b, v9
	v_add_f32_e32 v8, v33, v8
	v_exp_f32_e32 v24, v9
	v_sub_f32_e32 v9, v90, v98
	v_add_f32_e32 v8, v16, v8
	v_mul_f32_e32 v9, 0x3fb8aa3b, v9
	v_add_f32_e32 v8, v18, v8
	v_exp_f32_e32 v23, v9
	v_sub_f32_e32 v9, v91, v98
	v_add_f32_e32 v8, v17, v8
	v_mul_f32_e32 v9, 0x3fb8aa3b, v9
	v_add_f32_e32 v8, v19, v8
	v_exp_f32_e32 v25, v9
	v_add_f32_e32 v8, v22, v8
	v_add_f32_e32 v8, v24, v8
	v_add_f32_e32 v8, v23, v8
	v_add_f32_e32 v12, v25, v8
	v_sub_f32_e32 v8, v92, v98
	v_sub_f32_e32 v9, v93, v98
	v_mul_f32_e32 v8, 0x3fb8aa3b, v8
	v_mul_f32_e32 v9, 0x3fb8aa3b, v9
	v_exp_f32_e32 v8, v8
	v_exp_f32_e32 v10, v9
	v_sub_f32_e32 v9, v58, v98
	v_mul_f32_e32 v9, 0x3fb8aa3b, v9
	v_sub_f32_e32 v11, v59, v98
	v_exp_f32_e32 v9, v9
	v_mul_f32_e32 v11, 0x3fb8aa3b, v11
	v_exp_f32_e32 v11, v11
	v_add_f32_e32 v12, v8, v12
	v_add_f32_e32 v12, v10, v12
	v_add_f32_e32 v12, v9, v12
	v_add_f32_e32 v20, v11, v12
	v_sub_f32_e32 v12, v94, v98
	v_sub_f32_e32 v13, v95, v98
	v_mul_f32_e32 v12, 0x3fb8aa3b, v12
	v_mul_f32_e32 v13, 0x3fb8aa3b, v13
	v_exp_f32_e32 v12, v12
	v_exp_f32_e32 v14, v13
	v_sub_f32_e32 v13, v96, v98
	v_mul_f32_e32 v13, 0x3fb8aa3b, v13
	v_sub_f32_e32 v15, v97, v98
	v_exp_f32_e32 v13, v13
	v_mul_f32_e32 v15, 0x3fb8aa3b, v15
	v_exp_f32_e32 v15, v15
	v_add_f32_e32 v20, v12, v20
	v_add_f32_e32 v20, v14, v20
	v_add_f32_e32 v20, v13, v20
	v_add_f32_e32 v20, v15, v20
	ds_bpermute_b32 v21, v64, v20
	v_sub_f32_e32 v58, v68, v98
	v_mul_f32_e32 v58, 0x3fb8aa3b, v58
	v_exp_f32_e32 v58, v58
	s_waitcnt lgkmcnt(0)
	v_add_f32_e32 v20, v20, v21
	ds_bpermute_b32 v21, v65, v20
	s_waitcnt lgkmcnt(0)
	v_add_f32_e32 v20, v20, v21
	v_add_f32_e32 v20, v58, v20
	v_div_scale_f32 v21, vcc, v20, v20, 1.0
	v_rcp_f32_e32 v58, v21
	v_div_scale_f32 v59, vcc, 1.0, v20, 1.0
	v_add_u32_e32 v75, 0x9000, v67
	v_fma_f32 v68, -v21, v58, 1.0
	v_fmac_f32_e32 v58, v68, v58
	v_mul_f32_e32 v68, v59, v58
	v_fma_f32 v69, -v21, v68, v59
	v_fmac_f32_e32 v68, v69, v58
	v_fma_f32 v21, -v21, v68, v59
	v_div_fmas_f32 v21, v21, v58, v68
	v_div_fixup_f32 v20, v21, v20, 1.0
	v_pk_mul_f32 v[52:53], v[52:53], v[20:21] op_sel_hi:[1,0]
	v_pk_mul_f32 v[56:57], v[56:57], v[20:21] op_sel_hi:[1,0]
	v_pk_mul_f32 v[50:51], v[50:51], v[20:21] op_sel_hi:[1,0]
	v_pk_mul_f32 v[54:55], v[54:55], v[20:21] op_sel_hi:[1,0]
	v_bfe_u32 v21, v57, 16, 1
	v_bfe_u32 v58, v56, 16, 1
	v_bfe_u32 v59, v53, 16, 1
	v_bfe_u32 v68, v52, 16, 1
	v_add3_u32 v68, v52, v68, s33
	v_add3_u32 v59, v53, v59, s33
	v_add3_u32 v56, v56, v58, s33
	v_add3_u32 v21, v57, v21, s33
	v_bfe_u32 v52, v50, 16, 1
	v_bfe_u32 v53, v51, 16, 1
	v_bfe_u32 v57, v54, 16, 1
	v_bfe_u32 v58, v55, 16, 1
	v_add3_u32 v55, v55, v58, s33
	v_add3_u32 v54, v54, v57, s33
	v_add3_u32 v57, v51, v53, s33
	v_add3_u32 v58, v50, v52, s33
	v_lshrrev_b32_e32 v58, 16, v58
	v_lshrrev_b32_e32 v69, 16, v57
	v_lshrrev_b32_e32 v54, 16, v54
	v_lshrrev_b32_e32 v55, 16, v55
	v_and_or_b32 v57, v21, s29, v55
	v_and_or_b32 v56, v56, s29, v54
	v_and_or_b32 v55, v59, s29, v69
	v_and_or_b32 v54, v68, s29, v58
	v_add_u32_e32 v58, 0xb000, v67
	v_add_u32_e32 v59, 0xd000, v67
	v_add_u32_e32 v81, 0xf000, v67
	ds_read2_b64 v[50:53], v75 offset1:4
	ds_read2_b64 v[68:71], v58 offset0:32 offset1:36
	ds_read2_b64 v[76:79], v59 offset0:64 offset1:68
	ds_read2_b64 v[82:85], v81 offset0:96 offset1:100
	s_waitcnt lgkmcnt(3)
	v_mfma_f32_16x16x32_bf16 v[50:53], v[50:53], v[54:57], 0
	s_waitcnt lgkmcnt(2)
	v_mfma_f32_16x16x32_bf16 v[68:71], v[68:71], v[54:57], 0
	s_waitcnt lgkmcnt(1)
	v_mfma_f32_16x16x32_bf16 v[76:79], v[76:79], v[54:57], 0
	s_waitcnt lgkmcnt(0)
	v_mfma_f32_16x16x32_bf16 v[54:57], v[82:85], v[54:57], 0
	ds_read2_b64 v[116:119], v75 offset0:8 offset1:12
	ds_read2_b64 v[120:123], v58 offset0:40 offset1:44
	ds_read2_b64 v[124:127], v59 offset0:72 offset1:76
	ds_read2_b64 v[128:131], v81 offset0:104 offset1:108
	v_mul_f32_e64 v44, v44, v20
	v_mul_f32_e64 v45, v45, v20
	v_pk_mul_f32 v[48:49], v[48:49], v[20:21] op_sel_hi:[1,0]
	v_pk_mul_f32 v[42:43], v[42:43], v[20:21] op_sel_hi:[1,0]
	v_pk_mul_f32 v[46:47], v[46:47], v[20:21] op_sel_hi:[1,0]
	v_bfe_u32 v21, v49, 16, 1
	v_bfe_u32 v82, v48, 16, 1
	v_bfe_u32 v83, v45, 16, 1
	v_bfe_u32 v84, v44, 16, 1
	v_add3_u32 v84, v44, v84, s33
	v_add3_u32 v83, v45, v83, s33
	v_add3_u32 v48, v48, v82, s33
	v_add3_u32 v21, v49, v21, s33
	v_bfe_u32 v44, v42, 16, 1
	v_bfe_u32 v45, v43, 16, 1
	v_bfe_u32 v49, v46, 16, 1
	v_bfe_u32 v82, v47, 16, 1
	v_add3_u32 v47, v47, v82, s33
	v_add3_u32 v46, v46, v49, s33
	v_add3_u32 v49, v43, v45, s33
	v_add3_u32 v82, v42, v44, s33
	v_lshrrev_b32_e32 v82, 16, v82
	v_lshrrev_b32_e32 v85, 16, v49
	v_lshrrev_b32_e32 v46, 16, v46
	v_lshrrev_b32_e32 v47, 16, v47
	v_and_or_b32 v49, v21, s29, v47
	v_and_or_b32 v48, v48, s29, v46
	v_and_or_b32 v47, v83, s29, v85
	v_and_or_b32 v46, v84, s29, v82
	s_waitcnt lgkmcnt(3)
	s_nop 1
	v_mfma_f32_16x16x32_bf16 v[42:45], v[116:119], v[46:49], v[50:53]
	s_waitcnt lgkmcnt(2)
	v_mfma_f32_16x16x32_bf16 v[50:53], v[120:123], v[46:49], v[68:71]
	s_waitcnt lgkmcnt(1)
	v_mfma_f32_16x16x32_bf16 v[68:71], v[124:127], v[46:49], v[76:79]
	s_waitcnt lgkmcnt(0)
	v_mfma_f32_16x16x32_bf16 v[46:49], v[128:131], v[46:49], v[54:57]
	ds_read2_b64 v[132:135], v75 offset0:16 offset1:20
	ds_read2_b64 v[136:139], v58 offset0:48 offset1:52
	ds_read2_b64 v[140:143], v59 offset0:80 offset1:84
	ds_read2_b64 v[144:147], v81 offset0:112 offset1:116
	v_mul_f32_e64 v36, v36, v20
	v_mul_f32_e64 v37, v37, v20
	v_pk_mul_f32 v[40:41], v[40:41], v[20:21] op_sel_hi:[1,0]
	v_pk_mul_f32 v[34:35], v[34:35], v[20:21] op_sel_hi:[1,0]
	v_pk_mul_f32 v[38:39], v[38:39], v[20:21] op_sel_hi:[1,0]
	v_bfe_u32 v21, v41, 16, 1
	v_bfe_u32 v54, v40, 16, 1
	v_bfe_u32 v55, v37, 16, 1
	v_bfe_u32 v56, v36, 16, 1
	v_add3_u32 v56, v36, v56, s33
	v_add3_u32 v55, v37, v55, s33
	v_add3_u32 v40, v40, v54, s33
	v_add3_u32 v21, v41, v21, s33
	v_bfe_u32 v36, v34, 16, 1
	v_bfe_u32 v37, v35, 16, 1
	v_bfe_u32 v41, v38, 16, 1
	v_bfe_u32 v54, v39, 16, 1
	v_add3_u32 v39, v39, v54, s33
	v_add3_u32 v38, v38, v41, s33
	v_add3_u32 v41, v35, v37, s33
	v_add3_u32 v54, v34, v36, s33
	v_lshrrev_b32_e32 v54, 16, v54
	v_lshrrev_b32_e32 v57, 16, v41
	v_lshrrev_b32_e32 v38, 16, v38
	v_lshrrev_b32_e32 v39, 16, v39
	v_and_or_b32 v41, v21, s29, v39
	v_and_or_b32 v40, v40, s29, v38
	v_and_or_b32 v39, v55, s29, v57
	v_and_or_b32 v38, v56, s29, v54
	s_waitcnt lgkmcnt(3)
	s_nop 1
	v_mfma_f32_16x16x32_bf16 v[34:37], v[132:135], v[38:41], v[42:45]
	s_waitcnt lgkmcnt(2)
	v_mfma_f32_16x16x32_bf16 v[42:45], v[136:139], v[38:41], v[50:53]
	s_waitcnt lgkmcnt(1)
	v_mfma_f32_16x16x32_bf16 v[50:53], v[140:143], v[38:41], v[68:71]
	s_waitcnt lgkmcnt(0)
	v_mfma_f32_16x16x32_bf16 v[38:41], v[144:147], v[38:41], v[46:49]
	ds_read2_b64 v[116:119], v75 offset0:24 offset1:28
	ds_read2_b64 v[120:123], v58 offset0:56 offset1:60
	ds_read2_b64 v[124:127], v59 offset0:88 offset1:92
	ds_read2_b64 v[128:131], v81 offset0:120 offset1:124
	v_mul_f32_e64 v28, v28, v20
	v_mul_f32_e64 v29, v29, v20
	v_pk_mul_f32 v[32:33], v[32:33], v[20:21] op_sel_hi:[1,0]
	v_pk_mul_f32 v[26:27], v[26:27], v[20:21] op_sel_hi:[1,0]
	v_pk_mul_f32 v[30:31], v[30:31], v[20:21] op_sel_hi:[1,0]
	v_bfe_u32 v21, v33, 16, 1
	v_bfe_u32 v46, v32, 16, 1
	v_bfe_u32 v47, v29, 16, 1
	v_bfe_u32 v48, v28, 16, 1
	v_add3_u32 v48, v28, v48, s33
	v_add3_u32 v47, v29, v47, s33
	v_add3_u32 v32, v32, v46, s33
	v_add3_u32 v21, v33, v21, s33
	v_bfe_u32 v28, v26, 16, 1
	v_bfe_u32 v29, v27, 16, 1
	v_bfe_u32 v33, v30, 16, 1
	v_bfe_u32 v46, v31, 16, 1
	v_add3_u32 v31, v31, v46, s33
	v_add3_u32 v30, v30, v33, s33
	v_add3_u32 v33, v27, v29, s33
	v_add3_u32 v46, v26, v28, s33
	v_lshrrev_b32_e32 v46, 16, v46
	v_lshrrev_b32_e32 v49, 16, v33
	v_lshrrev_b32_e32 v30, 16, v30
	v_lshrrev_b32_e32 v31, 16, v31
	v_and_or_b32 v33, v21, s29, v31
	v_and_or_b32 v32, v32, s29, v30
	v_and_or_b32 v31, v47, s29, v49
	v_and_or_b32 v30, v48, s29, v46
	s_waitcnt lgkmcnt(3)
	s_nop 1
	v_mfma_f32_16x16x32_bf16 v[26:29], v[116:119], v[30:33], v[34:37]
	s_waitcnt lgkmcnt(2)
	v_mfma_f32_16x16x32_bf16 v[34:37], v[120:123], v[30:33], v[42:45]
	s_waitcnt lgkmcnt(1)
	v_mfma_f32_16x16x32_bf16 v[42:45], v[124:127], v[30:33], v[50:53]
	s_waitcnt lgkmcnt(0)
	v_mfma_f32_16x16x32_bf16 v[30:33], v[128:131], v[30:33], v[38:41]
	ds_read2_b64 v[132:135], v75 offset0:32 offset1:36
	ds_read2_b64 v[136:139], v58 offset0:64 offset1:68
	ds_read2_b64 v[140:143], v59 offset0:96 offset1:100
	ds_read2_b64 v[144:147], v81 offset0:128 offset1:132
	v_mul_f32_e64 v18, v18, v20
	v_mul_f32_e64 v19, v19, v20
	v_pk_mul_f32 v[24:25], v[24:25], v[20:21] op_sel_hi:[1,0]
	v_pk_mul_f32 v[16:17], v[16:17], v[20:21] op_sel_hi:[1,0]
	v_pk_mul_f32 v[22:23], v[22:23], v[20:21] op_sel_hi:[1,0]
	v_bfe_u32 v21, v25, 16, 1
	v_bfe_u32 v38, v24, 16, 1
	v_bfe_u32 v39, v19, 16, 1
	v_bfe_u32 v40, v18, 16, 1
	v_add3_u32 v40, v18, v40, s33
	v_add3_u32 v39, v19, v39, s33
	v_add3_u32 v24, v24, v38, s33
	v_add3_u32 v21, v25, v21, s33
	v_bfe_u32 v18, v16, 16, 1
	v_bfe_u32 v19, v17, 16, 1
	v_bfe_u32 v25, v22, 16, 1
	v_bfe_u32 v38, v23, 16, 1
	v_add3_u32 v23, v23, v38, s33
	v_add3_u32 v22, v22, v25, s33
	v_add3_u32 v25, v17, v19, s33
	v_add3_u32 v38, v16, v18, s33
	v_lshrrev_b32_e32 v38, 16, v38
	v_lshrrev_b32_e32 v41, 16, v25
	v_lshrrev_b32_e32 v22, 16, v22
	v_lshrrev_b32_e32 v23, 16, v23
	v_and_or_b32 v25, v21, s29, v23
	v_and_or_b32 v24, v24, s29, v22
	v_and_or_b32 v23, v39, s29, v41
	v_and_or_b32 v22, v40, s29, v38
	s_waitcnt lgkmcnt(3)
	s_nop 1
	v_mfma_f32_16x16x32_bf16 v[16:19], v[132:135], v[22:25], v[26:29]
	s_waitcnt lgkmcnt(2)
	v_mfma_f32_16x16x32_bf16 v[26:29], v[136:139], v[22:25], v[34:37]
	s_waitcnt lgkmcnt(1)
	v_mfma_f32_16x16x32_bf16 v[34:37], v[140:143], v[22:25], v[42:45]
	s_waitcnt lgkmcnt(0)
	v_mfma_f32_16x16x32_bf16 v[30:33], v[144:147], v[22:25], v[30:33]
	ds_read2_b64 v[116:119], v75 offset0:40 offset1:44
	ds_read2_b64 v[120:123], v58 offset0:72 offset1:76
	ds_read2_b64 v[124:127], v59 offset0:104 offset1:108
	ds_read2_b64 v[128:131], v81 offset0:136 offset1:140
	v_mul_f32_e64 v10, v10, v20
	v_mul_f32_e64 v11, v11, v20
	v_pk_mul_f32 v[14:15], v[14:15], v[20:21] op_sel_hi:[1,0]
	v_pk_mul_f32 v[8:9], v[8:9], v[20:21] op_sel_hi:[1,0]
	v_pk_mul_f32 v[12:13], v[12:13], v[20:21] op_sel_hi:[1,0]
	v_bfe_u32 v20, v15, 16, 1
	v_bfe_u32 v21, v14, 16, 1
	v_bfe_u32 v22, v11, 16, 1
	v_bfe_u32 v23, v10, 16, 1
	v_add3_u32 v23, v10, v23, s33
	v_add3_u32 v22, v11, v22, s33
	v_add3_u32 v14, v14, v21, s33
	v_add3_u32 v15, v15, v20, s33
	v_bfe_u32 v10, v8, 16, 1
	v_bfe_u32 v11, v9, 16, 1
	v_bfe_u32 v20, v12, 16, 1
	v_bfe_u32 v21, v13, 16, 1
	v_add3_u32 v13, v13, v21, s33
	v_add3_u32 v12, v12, v20, s33
	v_add3_u32 v20, v9, v11, s33
	v_add3_u32 v21, v8, v10, s33
	v_lshrrev_b32_e32 v21, 16, v21
	v_lshrrev_b32_e32 v20, 16, v20
	v_lshrrev_b32_e32 v12, 16, v12
	v_lshrrev_b32_e32 v13, 16, v13
	v_and_or_b32 v41, v15, s29, v13
	v_and_or_b32 v40, v14, s29, v12
	v_and_or_b32 v39, v22, s29, v20
	v_and_or_b32 v38, v23, s29, v21
	s_waitcnt lgkmcnt(3)
	s_nop 1
	v_mfma_f32_16x16x32_bf16 v[20:23], v[116:119], v[38:41], v[16:19]
	s_waitcnt lgkmcnt(2)
	v_mfma_f32_16x16x32_bf16 v[16:19], v[120:123], v[38:41], v[26:29]
	s_waitcnt lgkmcnt(1)
	v_mfma_f32_16x16x32_bf16 v[12:15], v[124:127], v[38:41], v[34:37]
	s_waitcnt lgkmcnt(0)
	v_mfma_f32_16x16x32_bf16 v[8:11], v[128:131], v[38:41], v[30:33]
	s_and_saveexec_b64 vcc, s[0:1]
	s_cbranch_execz .LBB0_311
	v_bfe_u32 v26, v20, 16, 1
	v_add3_u32 v20, v20, v26, s33
	v_bfe_u32 v26, v21, 16, 1
	v_add3_u32 v21, v21, v26, s33
	v_lshrrev_b32_e32 v20, 16, v20
	v_and_or_b32 v20, v21, s29, v20
	v_bfe_u32 v21, v22, 16, 1
	v_add3_u32 v21, v22, v21, s33
	v_bfe_u32 v22, v23, 16, 1
	v_add3_u32 v22, v23, v22, s33
	v_lshrrev_b32_e32 v21, 16, v21
	v_lshl_add_u64 v[24:25], v[60:61], 0, s[2:3]
	v_and_or_b32 v21, v22, s29, v21
	global_store_dwordx2 v[24:25], v[20:21], off
	v_bfe_u32 v20, v16, 16, 1
	v_add3_u32 v16, v16, v20, s33
	v_bfe_u32 v20, v17, 16, 1
	v_add3_u32 v17, v17, v20, s33
	v_lshrrev_b32_e32 v16, 16, v16
	v_and_or_b32 v16, v17, s29, v16
	v_bfe_u32 v17, v18, 16, 1
	v_add3_u32 v17, v18, v17, s33
	v_bfe_u32 v18, v19, 16, 1
	v_add3_u32 v18, v19, v18, s33
	v_lshrrev_b32_e32 v17, 16, v17
	v_and_or_b32 v17, v18, s29, v17
	global_store_dwordx2 v[24:25], v[16:17], off offset:32
	v_bfe_u32 v16, v12, 16, 1
	v_add3_u32 v12, v12, v16, s33
	v_bfe_u32 v16, v13, 16, 1
	v_add3_u32 v13, v13, v16, s33
	v_lshrrev_b32_e32 v12, 16, v12
	v_and_or_b32 v12, v13, s29, v12
	v_bfe_u32 v13, v14, 16, 1
	v_add3_u32 v13, v14, v13, s33
	v_bfe_u32 v14, v15, 16, 1
	v_add3_u32 v14, v15, v14, s33
	v_lshrrev_b32_e32 v13, 16, v13
	v_and_or_b32 v13, v14, s29, v13
	global_store_dwordx2 v[24:25], v[12:13], off offset:64
	v_bfe_u32 v12, v8, 16, 1
	v_add3_u32 v8, v8, v12, s33
	v_bfe_u32 v12, v9, 16, 1
	v_add3_u32 v9, v9, v12, s33
	v_lshrrev_b32_e32 v8, 16, v8
	v_and_or_b32 v8, v9, s29, v8
	v_bfe_u32 v9, v10, 16, 1
	v_add3_u32 v9, v10, v9, s33
	v_bfe_u32 v10, v11, 16, 1
	v_add3_u32 v10, v11, v10, s33
	v_lshrrev_b32_e32 v9, 16, v9
	v_and_or_b32 v9, v10, s29, v9
	global_store_dwordx2 v[24:25], v[8:9], off offset:96
	s_branch .LBB0_311
